# GEMM K-loop headers aligned to 64 bytes (s_nop padding)
# speedup vs baseline: 1.0002x; 1.0002x over previous
; #define PG8_STAGE(bufoff, gbase, voff) do { _Pragma("unroll") for (int _i = 0; _i < 2; ++_i) \
;         __builtin_amdgcn_global_load_lds((const unsigned*)((const char*)(gbase) + (voff)[_i]), (LAS unsigned*)(lds + (bufoff) + ldsw + _i * 8192), 16, 0, 0); } while (0)
; #define PG8_LDA(dst, b, h) do { _Pragma("unroll") for (int m = 0; m < 4; ++m) _Pragma("unroll") for (int k = 0; k < 2; ++k) dst[m][k] = *(const LAS bf16x8*)(lds + PG8_SA(b, h) + aoff + m * 2048 + k * 1024); } while (0)
; #define PG8_LDB(dst, b, h) do { _Pragma("unroll") for (int n = 0; n < 2; ++n) _Pragma("unroll") for (int k = 0; k < 2; ++k) dst[n][k] = *(const LAS bf16x8*)(lds + PG8_SB(b, h) + boff + n * 2048 + k * 1024); } while (0)
; #define PG8_MMA(ai, bj, At, Bt) do { __builtin_amdgcn_s_setprio(1); _Pragma("unroll") for (int m = 0; m < 4; ++m) _Pragma("unroll") for (int n = 0; n < 2; ++n) _Pragma("unroll") for (int k = 0; k < 2; ++k) \
;         acc[ai][bj][m][n] = __builtin_amdgcn_mfma_f32_16x16x32_bf16(Bt[n][k], At[m][k], acc[ai][bj][m][n], 0, 0, 0); __builtin_amdgcn_s_setprio(0); } while (0)
; #define PG8_WAIT_V(n) asm volatile("s_waitcnt vmcnt(" #n ")" ::: "memory")
; #define PG8_WAIT_L(n) asm volatile("s_waitcnt lgkmcnt(" #n ")" ::: "memory")
; #define PG8_BAR __builtin_amdgcn_s_barrier()
; #define PG8_SCHED __builtin_amdgcn_sched_barrier(0)
; template <class Epi, class Sched>
; DI void gemm_phase(LAS unsigned char* lds, const Gemm g, const Sched& S, const Epi& E) {
;     ...
;             PG8_LDB(B0, 0, 0); PG8_LDB(B1, 0, 1); PG8_SCHED; PG8_LDA(At, 0, 0); PG8_STAGE(PG8_SA(1, 1), a1 + hstepA, voffA);
;             PG8_WAIT_V(8); PG8_WAIT_L(0); PG8_BAR; PG8_MMA(0, 0, At, B0); PG8_MMA(0, 1, At, B1); PG8_BAR; PG8_SCHED;
;             PG8_LDA(At, 0, 1); PG8_STAGE(PG8_SB(0, 0), b2, voffB); PG8_STAGE(PG8_SB(0, 1), b2 + hstepB, voffB); PG8_STAGE(PG8_SA(0, 0), a2, voffA);
;             PG8_WAIT_V(8); PG8_WAIT_L(0); PG8_BAR; PG8_MMA(1, 0, At, B0); PG8_MMA(1, 1, At, B1); PG8_BAR; PG8_SCHED;
;             PG8_LDB(B0, 1, 0); PG8_LDB(B1, 1, 1); PG8_SCHED; PG8_LDA(At, 1, 0); PG8_STAGE(PG8_SA(0, 1), a2 + hstepA, voffA);
;             PG8_WAIT_V(8); PG8_WAIT_L(0); PG8_BAR; PG8_MMA(0, 0, At, B0); PG8_MMA(0, 1, At, B1); PG8_BAR; PG8_SCHED;
.Lpk0_w2:
	s_mov_b32 s99, 0
	s_waitcnt lgkmcnt(0)
	s_barrier
	s_setprio 1
	v_mfma_f32_16x16x32_bf16 v[62:65], v[168:171], v[202:205], 0
	v_mfma_f32_16x16x32_bf16 v[54:57], v[176:179], v[202:205], 0
	v_mfma_f32_16x16x32_bf16 v[46:49], v[168:171], v[210:213], 0
	v_mfma_f32_16x16x32_bf16 v[38:41], v[176:179], v[210:213], 0
	v_mfma_f32_16x16x32_bf16 v[30:33], v[168:171], v[218:221], 0
	v_mfma_f32_16x16x32_bf16 v[22:25], v[176:179], v[218:221], 0
	v_mfma_f32_16x16x32_bf16 v[14:17], v[168:171], v[226:229], 0
	v_mfma_f32_16x16x32_bf16 v[6:9], v[176:179], v[226:229], 0
	v_mfma_f32_16x16x32_bf16 v[62:65], v[172:175], v[206:209], v[62:65]
	v_mfma_f32_16x16x32_bf16 v[54:57], v[180:183], v[206:209], v[54:57]
	v_mfma_f32_16x16x32_bf16 v[46:49], v[172:175], v[214:217], v[46:49]
	v_mfma_f32_16x16x32_bf16 v[38:41], v[180:183], v[214:217], v[38:41]
	v_mfma_f32_16x16x32_bf16 v[30:33], v[172:175], v[222:225], v[30:33]
	v_mfma_f32_16x16x32_bf16 v[22:25], v[180:183], v[222:225], v[22:25]
	v_mfma_f32_16x16x32_bf16 v[14:17], v[172:175], v[230:233], v[14:17]
	v_mfma_f32_16x16x32_bf16 v[6:9], v[180:183], v[230:233], v[6:9]
	v_mfma_f32_16x16x32_bf16 v[58:61], v[186:189], v[202:205], 0
	v_mfma_f32_16x16x32_bf16 v[50:53], v[194:197], v[202:205], 0
	v_mfma_f32_16x16x32_bf16 v[42:45], v[186:189], v[210:213], 0
	v_mfma_f32_16x16x32_bf16 v[34:37], v[194:197], v[210:213], 0
	v_mfma_f32_16x16x32_bf16 v[26:29], v[186:189], v[218:221], 0
	v_mfma_f32_16x16x32_bf16 v[18:21], v[194:197], v[218:221], 0
	v_mfma_f32_16x16x32_bf16 v[10:13], v[186:189], v[226:229], 0
	v_mfma_f32_16x16x32_bf16 v[2:5], v[194:197], v[226:229], 0
	v_mfma_f32_16x16x32_bf16 v[58:61], v[190:193], v[206:209], v[58:61]
	v_mfma_f32_16x16x32_bf16 v[50:53], v[198:201], v[206:209], v[50:53]
	v_mfma_f32_16x16x32_bf16 v[42:45], v[190:193], v[214:217], v[42:45]
	v_mfma_f32_16x16x32_bf16 v[34:37], v[198:201], v[214:217], v[34:37]
	v_mfma_f32_16x16x32_bf16 v[26:29], v[190:193], v[222:225], v[26:29]
	v_mfma_f32_16x16x32_bf16 v[18:21], v[198:201], v[222:225], v[18:21]
	v_mfma_f32_16x16x32_bf16 v[10:13], v[190:193], v[230:233], v[10:13]
	v_mfma_f32_16x16x32_bf16 v[2:5], v[198:201], v[230:233], v[2:5]
	s_setprio 0
	s_barrier
	s_add_i32 s66, 0, 0x18000
	v_add_u32_e32 v167, s66, v158
	s_add_i32 s67, 0, 0x1c000
	ds_read_b128 v[168:171], v167
	ds_read_b128 v[172:175], v167 offset:1024
	ds_read_b128 v[176:179], v167 offset:2048
	ds_read_b128 v[180:183], v167 offset:3072
	v_add_u32_e32 v167, s67, v158
	ds_read_b128 v[186:189], v167
	ds_read_b128 v[190:193], v167 offset:1024
	ds_read_b128 v[194:197], v167 offset:2048
	ds_read_b128 v[198:201], v167 offset:3072
	s_add_u32 s44, s44, 0x40000
	s_addc_u32 s45, s45, 0
	s_mov_b32 m0, s51
	v_lshl_add_u64 v[242:243], s[44:45], 0, v[136:137]
	ds_read_b128 v[202:205], v160 offset:32768
	ds_read_b128 v[206:209], v160 offset:33792
	ds_read_b128 v[210:213], v160 offset:34816
	ds_read_b128 v[214:217], v160 offset:35840
	ds_read_b128 v[218:221], v160 offset:36864
	ds_read_b128 v[222:225], v160 offset:37888
	ds_read_b128 v[226:229], v160 offset:38912
	ds_read_b128 v[230:233], v160 offset:39936
	global_load_lds_dwordx4 v[242:243], off
	v_lshl_add_u64 v[242:243], s[44:45], 0, v[132:133]
	s_mov_b32 m0, s52
	s_nop 0
	global_load_lds_dwordx4 v[242:243], off
	s_waitcnt vmcnt(8)
	s_waitcnt lgkmcnt(0)
	s_barrier
	s_setprio 1
	v_mfma_f32_16x16x32_bf16 v[126:129], v[168:171], v[202:205], v[126:129]
	v_mfma_f32_16x16x32_bf16 v[118:121], v[176:179], v[202:205], v[118:121]
	v_mfma_f32_16x16x32_bf16 v[110:113], v[168:171], v[210:213], v[110:113]
	v_mfma_f32_16x16x32_bf16 v[102:105], v[176:179], v[210:213], v[102:105]
	v_mfma_f32_16x16x32_bf16 v[94:97], v[168:171], v[218:221], v[94:97]
	v_mfma_f32_16x16x32_bf16 v[86:89], v[176:179], v[218:221], v[86:89]
	v_mfma_f32_16x16x32_bf16 v[78:81], v[168:171], v[226:229], v[78:81]
	v_mfma_f32_16x16x32_bf16 v[70:73], v[176:179], v[226:229], v[70:73]
	v_mfma_f32_16x16x32_bf16 v[126:129], v[172:175], v[206:209], v[126:129]
	v_mfma_f32_16x16x32_bf16 v[118:121], v[180:183], v[206:209], v[118:121]
	v_mfma_f32_16x16x32_bf16 v[110:113], v[172:175], v[214:217], v[110:113]
	v_mfma_f32_16x16x32_bf16 v[102:105], v[180:183], v[214:217], v[102:105]
	v_mfma_f32_16x16x32_bf16 v[94:97], v[172:175], v[222:225], v[94:97]
	v_mfma_f32_16x16x32_bf16 v[86:89], v[180:183], v[222:225], v[86:89]
	v_mfma_f32_16x16x32_bf16 v[78:81], v[172:175], v[230:233], v[78:81]
	v_mfma_f32_16x16x32_bf16 v[70:73], v[180:183], v[230:233], v[70:73]
	v_mfma_f32_16x16x32_bf16 v[122:125], v[186:189], v[202:205], v[122:125]
	v_mfma_f32_16x16x32_bf16 v[114:117], v[194:197], v[202:205], v[114:117]
	v_mfma_f32_16x16x32_bf16 v[106:109], v[186:189], v[210:213], v[106:109]
	v_mfma_f32_16x16x32_bf16 v[98:101], v[194:197], v[210:213], v[98:101]
	v_mfma_f32_16x16x32_bf16 v[90:93], v[186:189], v[218:221], v[90:93]
	v_mfma_f32_16x16x32_bf16 v[82:85], v[194:197], v[218:221], v[82:85]
	v_mfma_f32_16x16x32_bf16 v[74:77], v[186:189], v[226:229], v[74:77]
	v_mfma_f32_16x16x32_bf16 v[66:69], v[194:197], v[226:229], v[66:69]
	v_mfma_f32_16x16x32_bf16 v[122:125], v[190:193], v[206:209], v[122:125]
	v_mfma_f32_16x16x32_bf16 v[114:117], v[198:201], v[206:209], v[114:117]
	v_mfma_f32_16x16x32_bf16 v[106:109], v[190:193], v[214:217], v[106:109]
	v_mfma_f32_16x16x32_bf16 v[98:101], v[198:201], v[214:217], v[98:101]
	v_mfma_f32_16x16x32_bf16 v[90:93], v[190:193], v[222:225], v[90:93]
	v_mfma_f32_16x16x32_bf16 v[82:85], v[198:201], v[222:225], v[82:85]
	v_mfma_f32_16x16x32_bf16 v[74:77], v[190:193], v[230:233], v[74:77]
	v_mfma_f32_16x16x32_bf16 v[66:69], v[198:201], v[230:233], v[66:69]
	s_setprio 0
	s_barrier
; #define PG8_STAGE(bufoff, gbase, voff) do { _Pragma("unroll") for (int _i = 0; _i < 2; ++_i) \
;         __builtin_amdgcn_global_load_lds((const unsigned*)((const char*)(gbase) + (voff)[_i]), (LAS unsigned*)(lds + (bufoff) + ldsw + _i * 8192), 16, 0, 0); } while (0)
; #define PG8_LDA(dst, b, h) do { _Pragma("unroll") for (int m = 0; m < 4; ++m) _Pragma("unroll") for (int k = 0; k < 2; ++k) dst[m][k] = *(const LAS bf16x8*)(lds + PG8_SA(b, h) + aoff + m * 2048 + k * 1024); } while (0)
; #define PG8_MMA(ai, bj, At, Bt) do { __builtin_amdgcn_s_setprio(1); _Pragma("unroll") for (int m = 0; m < 4; ++m) _Pragma("unroll") for (int n = 0; n < 2; ++n) _Pragma("unroll") for (int k = 0; k < 2; ++k) \
;         acc[ai][bj][m][n] = __builtin_amdgcn_mfma_f32_16x16x32_bf16(Bt[n][k], At[m][k], acc[ai][bj][m][n], 0, 0, 0); __builtin_amdgcn_s_setprio(0); } while (0)
; #define PG8_WAIT_V(n) asm volatile("s_waitcnt vmcnt(" #n ")" ::: "memory")
; #define PG8_WAIT_L(n) asm volatile("s_waitcnt lgkmcnt(" #n ")" ::: "memory")
; #define PG8_BAR __builtin_amdgcn_s_barrier()
; #define PG8_SCHED __builtin_amdgcn_sched_barrier(0)
; template <class Epi, class Sched>
; DI void gemm_phase(LAS unsigned char* lds, const Gemm g, const Sched& S, const Epi& E) {
;     ...
;         for (int t = 0; t < nt; t += 2) {
;             const bool last = (t == nt - 2);
;             const char* a1 = cA + (size_t)(t + 1) * kstep;
;             const char* a2 = last ? nA : cA + (size_t)(t + 2) * kstep; const char* b2 = last ? nB : cB + (size_t)(t + 2) * kstep;
;             const char* a3 = a2 + kstep; const char* b3 = b2 + kstep;
;     ...
;             PG8_LDA(At, 1, 1); PG8_STAGE(PG8_SB(1, 0), b3, voffB); PG8_STAGE(PG8_SB(1, 1), b3 + hstepB, voffB); PG8_STAGE(PG8_SA(1, 0), a3, voffA);
;             PG8_WAIT_V(8); PG8_WAIT_L(0); PG8_BAR; PG8_MMA(1, 0, At, B0); PG8_MMA(1, 1, At, B1); PG8_BAR; PG8_SCHED;
	s_add_i32 s44, s66, s46
	v_lshl_add_u64 v[234:235], v[234:235], 0, s[16:17]
	s_mov_b32 m0, s44
	ds_read_b128 v[202:205], v160 offset:49152
	ds_read_b128 v[206:209], v160 offset:50176
	ds_read_b128 v[210:213], v160 offset:51200
	ds_read_b128 v[214:217], v160 offset:52224
	ds_read_b128 v[218:221], v160 offset:53248
	ds_read_b128 v[222:225], v160 offset:54272
	ds_read_b128 v[226:229], v160 offset:55296
	ds_read_b128 v[230:233], v160 offset:56320
	global_load_lds_dwordx4 v[234:235], off
	s_add_i32 m0, s44, 0x2000
	s_add_u32 s42, s42, 0x40080
	v_lshl_add_u64 v[234:235], v[236:237], 0, s[16:17]
	s_addc_u32 s43, s43, 0
	s_add_i32 s44, s67, s46
	global_load_lds_dwordx4 v[234:235], off
	v_lshl_add_u64 v[234:235], s[42:43], 0, v[134:135]
	s_mov_b32 m0, s44
	s_nop 0
	global_load_lds_dwordx4 v[234:235], off
	v_lshl_add_u64 v[234:235], s[42:43], 0, v[130:131]
	s_add_i32 m0, s44, 0x2000
	s_nop 0
	global_load_lds_dwordx4 v[234:235], off
	v_lshl_add_u64 v[234:235], v[238:239], 0, s[16:17]
	s_mov_b32 m0, s54
	s_nop 0
	global_load_lds_dwordx4 v[234:235], off
	v_lshl_add_u64 v[234:235], v[240:241], 0, s[16:17]
	s_mov_b32 m0, s55
	s_nop 0
	global_load_lds_dwordx4 v[234:235], off
	s_waitcnt vmcnt(8)
	s_waitcnt lgkmcnt(0)
	s_barrier
	s_setprio 1
	v_mfma_f32_16x16x32_bf16 v[62:65], v[168:171], v[202:205], v[62:65]
	v_mfma_f32_16x16x32_bf16 v[54:57], v[176:179], v[202:205], v[54:57]
	v_mfma_f32_16x16x32_bf16 v[46:49], v[168:171], v[210:213], v[46:49]
	v_mfma_f32_16x16x32_bf16 v[38:41], v[176:179], v[210:213], v[38:41]
	v_mfma_f32_16x16x32_bf16 v[30:33], v[168:171], v[218:221], v[30:33]
	v_mfma_f32_16x16x32_bf16 v[22:25], v[176:179], v[218:221], v[22:25]
	v_mfma_f32_16x16x32_bf16 v[14:17], v[168:171], v[226:229], v[14:17]
	v_mfma_f32_16x16x32_bf16 v[6:9], v[176:179], v[226:229], v[6:9]
	v_mfma_f32_16x16x32_bf16 v[62:65], v[172:175], v[206:209], v[62:65]
	v_mfma_f32_16x16x32_bf16 v[54:57], v[180:183], v[206:209], v[54:57]
	v_mfma_f32_16x16x32_bf16 v[46:49], v[172:175], v[214:217], v[46:49]
	v_mfma_f32_16x16x32_bf16 v[38:41], v[180:183], v[214:217], v[38:41]
	v_mfma_f32_16x16x32_bf16 v[30:33], v[172:175], v[222:225], v[30:33]
	v_mfma_f32_16x16x32_bf16 v[22:25], v[180:183], v[222:225], v[22:25]
	v_mfma_f32_16x16x32_bf16 v[14:17], v[172:175], v[230:233], v[14:17]
	v_mfma_f32_16x16x32_bf16 v[6:9], v[180:183], v[230:233], v[6:9]
	v_mfma_f32_16x16x32_bf16 v[58:61], v[186:189], v[202:205], v[58:61]
	v_mfma_f32_16x16x32_bf16 v[50:53], v[194:197], v[202:205], v[50:53]
	v_mfma_f32_16x16x32_bf16 v[42:45], v[186:189], v[210:213], v[42:45]
	v_mfma_f32_16x16x32_bf16 v[34:37], v[194:197], v[210:213], v[34:37]
	v_mfma_f32_16x16x32_bf16 v[26:29], v[186:189], v[218:221], v[26:29]
	v_mfma_f32_16x16x32_bf16 v[18:21], v[194:197], v[218:221], v[18:21]
	v_mfma_f32_16x16x32_bf16 v[10:13], v[186:189], v[226:229], v[10:13]
	v_mfma_f32_16x16x32_bf16 v[2:5], v[194:197], v[226:229], v[2:5]
	v_mfma_f32_16x16x32_bf16 v[58:61], v[190:193], v[206:209], v[58:61]
	v_mfma_f32_16x16x32_bf16 v[50:53], v[198:201], v[206:209], v[50:53]
	v_mfma_f32_16x16x32_bf16 v[42:45], v[190:193], v[214:217], v[42:45]
	v_mfma_f32_16x16x32_bf16 v[34:37], v[198:201], v[214:217], v[34:37]
	v_mfma_f32_16x16x32_bf16 v[26:29], v[190:193], v[222:225], v[26:29]
	v_mfma_f32_16x16x32_bf16 v[18:21], v[198:201], v[222:225], v[18:21]
	v_mfma_f32_16x16x32_bf16 v[10:13], v[190:193], v[230:233], v[10:13]
	v_mfma_f32_16x16x32_bf16 v[2:5], v[198:201], v[230:233], v[2:5]
	s_setprio 0
	s_barrier
	s_add_i32 s65, s65, 2
	s_add_u32 s40, s40, 0x100
	s_addc_u32 s41, s41, 0
	s_add_u32 s63, s63, 0x100
	s_addc_u32 s64, s64, 0
	s_cmp_gt_u32 s65, 13
	.p2alignl 6, 3212836864

; #define PG8_STAGE(bufoff, gbase, voff) do { _Pragma("unroll") for (int _i = 0; _i < 2; ++_i) \
;         __builtin_amdgcn_global_load_lds((const unsigned*)((const char*)(gbase) + (voff)[_i]), (LAS unsigned*)(lds + (bufoff) + ldsw + _i * 8192), 16, 0, 0); } while (0)
; #define PG8_LDA(dst, b, h) do { _Pragma("unroll") for (int m = 0; m < 4; ++m) _Pragma("unroll") for (int k = 0; k < 2; ++k) dst[m][k] = *(const LAS bf16x8*)(lds + PG8_SA(b, h) + aoff + m * 2048 + k * 1024); } while (0)
; #define PG8_LDB(dst, b, h) do { _Pragma("unroll") for (int n = 0; n < 2; ++n) _Pragma("unroll") for (int k = 0; k < 2; ++k) dst[n][k] = *(const LAS bf16x8*)(lds + PG8_SB(b, h) + boff + n * 2048 + k * 1024); } while (0)
; #define PG8_MMA(ai, bj, At, Bt) do { __builtin_amdgcn_s_setprio(1); _Pragma("unroll") for (int m = 0; m < 4; ++m) _Pragma("unroll") for (int n = 0; n < 2; ++n) _Pragma("unroll") for (int k = 0; k < 2; ++k) \
;         acc[ai][bj][m][n] = __builtin_amdgcn_mfma_f32_16x16x32_bf16(Bt[n][k], At[m][k], acc[ai][bj][m][n], 0, 0, 0); __builtin_amdgcn_s_setprio(0); } while (0)
; #define PG8_WAIT_V(n) asm volatile("s_waitcnt vmcnt(" #n ")" ::: "memory")
; #define PG8_WAIT_L(n) asm volatile("s_waitcnt lgkmcnt(" #n ")" ::: "memory")
; #define PG8_BAR __builtin_amdgcn_s_barrier()
; #define PG8_SCHED __builtin_amdgcn_sched_barrier(0)
; template <class Epi, class Sched>
; DI void gemm_phase(LAS unsigned char* lds, const Gemm g, const Sched& S, const Epi& E) {
;     ...
;             PG8_LDB(B0, 0, 0); PG8_LDB(B1, 0, 1); PG8_SCHED; PG8_LDA(At, 0, 0); PG8_STAGE(PG8_SA(1, 1), a1 + hstepA, voffA);
;             PG8_WAIT_V(8); PG8_WAIT_L(0); PG8_BAR; PG8_MMA(0, 0, At, B0); PG8_MMA(0, 1, At, B1); PG8_BAR; PG8_SCHED;
;             PG8_LDA(At, 0, 1); PG8_STAGE(PG8_SB(0, 0), b2, voffB); PG8_STAGE(PG8_SB(0, 1), b2 + hstepB, voffB); PG8_STAGE(PG8_SA(0, 0), a2, voffA);
;             PG8_WAIT_V(8); PG8_WAIT_L(0); PG8_BAR; PG8_MMA(1, 0, At, B0); PG8_MMA(1, 1, At, B1); PG8_BAR; PG8_SCHED;
;             PG8_LDB(B0, 1, 0); PG8_LDB(B1, 1, 1); PG8_SCHED; PG8_LDA(At, 1, 0); PG8_STAGE(PG8_SA(0, 1), a2 + hstepA, voffA);
;             PG8_WAIT_V(8); PG8_WAIT_L(0); PG8_BAR; PG8_MMA(0, 0, At, B0); PG8_MMA(0, 1, At, B1); PG8_BAR; PG8_SCHED;
.Lpk1_w2:
	s_mov_b32 s99, 0
	s_waitcnt lgkmcnt(0)
	s_barrier
	s_setprio 1
	v_mfma_f32_16x16x32_bf16 v[62:65], v[148:151], v[190:193], 0
	v_mfma_f32_16x16x32_bf16 v[58:61], v[162:165], v[190:193], 0
	v_mfma_f32_16x16x32_bf16 v[46:49], v[148:151], v[198:201], 0
	v_mfma_f32_16x16x32_bf16 v[42:45], v[162:165], v[198:201], 0
	v_mfma_f32_16x16x32_bf16 v[30:33], v[148:151], v[206:209], 0
	v_mfma_f32_16x16x32_bf16 v[26:29], v[162:165], v[206:209], 0
	v_mfma_f32_16x16x32_bf16 v[14:17], v[148:151], v[214:217], 0
	v_mfma_f32_16x16x32_bf16 v[10:13], v[162:165], v[214:217], 0
	v_mfma_f32_16x16x32_bf16 v[62:65], v[158:161], v[194:197], v[62:65]
	v_mfma_f32_16x16x32_bf16 v[58:61], v[166:169], v[194:197], v[58:61]
	v_mfma_f32_16x16x32_bf16 v[46:49], v[158:161], v[202:205], v[46:49]
	v_mfma_f32_16x16x32_bf16 v[42:45], v[166:169], v[202:205], v[42:45]
	v_mfma_f32_16x16x32_bf16 v[30:33], v[158:161], v[210:213], v[30:33]
	v_mfma_f32_16x16x32_bf16 v[26:29], v[166:169], v[210:213], v[26:29]
	v_mfma_f32_16x16x32_bf16 v[14:17], v[158:161], v[218:221], v[14:17]
	v_mfma_f32_16x16x32_bf16 v[10:13], v[166:169], v[218:221], v[10:13]
	v_mfma_f32_16x16x32_bf16 v[54:57], v[170:173], v[190:193], 0
	v_mfma_f32_16x16x32_bf16 v[50:53], v[178:181], v[190:193], 0
	v_mfma_f32_16x16x32_bf16 v[38:41], v[170:173], v[198:201], 0
	v_mfma_f32_16x16x32_bf16 v[34:37], v[178:181], v[198:201], 0
	v_mfma_f32_16x16x32_bf16 v[22:25], v[170:173], v[206:209], 0
	v_mfma_f32_16x16x32_bf16 v[18:21], v[178:181], v[206:209], 0
	v_mfma_f32_16x16x32_bf16 v[6:9], v[170:173], v[214:217], 0
	v_mfma_f32_16x16x32_bf16 v[2:5], v[178:181], v[214:217], 0
	v_mfma_f32_16x16x32_bf16 v[54:57], v[174:177], v[194:197], v[54:57]
	v_mfma_f32_16x16x32_bf16 v[50:53], v[186:189], v[194:197], v[50:53]
	v_mfma_f32_16x16x32_bf16 v[38:41], v[174:177], v[202:205], v[38:41]
	v_mfma_f32_16x16x32_bf16 v[34:37], v[186:189], v[202:205], v[34:37]
	v_mfma_f32_16x16x32_bf16 v[22:25], v[174:177], v[210:213], v[22:25]
	v_mfma_f32_16x16x32_bf16 v[18:21], v[186:189], v[210:213], v[18:21]
	v_mfma_f32_16x16x32_bf16 v[6:9], v[174:177], v[218:221], v[6:9]
	v_mfma_f32_16x16x32_bf16 v[2:5], v[186:189], v[218:221], v[2:5]
	s_setprio 0
	s_barrier
	s_add_i32 s63, 0, 0x18000
	s_add_i32 s64, 0, 0x1c000
	v_add_u32_e32 v166, s63, v152
	v_add_u32_e32 v185, s64, v152
	ds_read_b128 v[148:151], v166
	ds_read_b128 v[158:161], v166 offset:1024
	ds_read_b128 v[162:165], v166 offset:2048
	ds_read_b128 v[166:169], v166 offset:3072
	ds_read_b128 v[170:173], v185
	ds_read_b128 v[174:177], v185 offset:1024
	ds_read_b128 v[178:181], v185 offset:2048
	ds_read_b128 v[186:189], v185 offset:3072
	s_add_u32 s40, s40, 0xb0000
	s_addc_u32 s41, s41, 0
	s_mov_b32 m0, s47
	v_lshl_add_u64 v[228:229], s[40:41], 0, v[130:131]
	ds_read_b128 v[190:193], v156 offset:32768
	ds_read_b128 v[194:197], v156 offset:33792
	ds_read_b128 v[198:201], v156 offset:34816
	ds_read_b128 v[202:205], v156 offset:35840
	ds_read_b128 v[206:209], v156 offset:36864
	ds_read_b128 v[210:213], v156 offset:37888
	ds_read_b128 v[214:217], v156 offset:38912
	ds_read_b128 v[218:221], v156 offset:39936
	global_load_lds_dwordx4 v[228:229], off
	v_lshl_add_u64 v[228:229], s[40:41], 0, v[134:135]
	s_mov_b32 m0, s48
	s_nop 0
	global_load_lds_dwordx4 v[228:229], off
	s_waitcnt vmcnt(8)
	s_waitcnt lgkmcnt(0)
	s_barrier
	s_setprio 1
	v_mfma_f32_16x16x32_bf16 v[126:129], v[148:151], v[190:193], v[126:129]
	v_mfma_f32_16x16x32_bf16 v[122:125], v[162:165], v[190:193], v[122:125]
	v_mfma_f32_16x16x32_bf16 v[110:113], v[148:151], v[198:201], v[110:113]
	v_mfma_f32_16x16x32_bf16 v[106:109], v[162:165], v[198:201], v[106:109]
	v_mfma_f32_16x16x32_bf16 v[94:97], v[148:151], v[206:209], v[94:97]
	v_mfma_f32_16x16x32_bf16 v[90:93], v[162:165], v[206:209], v[90:93]
	v_mfma_f32_16x16x32_bf16 v[78:81], v[148:151], v[214:217], v[78:81]
	v_mfma_f32_16x16x32_bf16 v[74:77], v[162:165], v[214:217], v[74:77]
	v_mfma_f32_16x16x32_bf16 v[126:129], v[158:161], v[194:197], v[126:129]
	v_mfma_f32_16x16x32_bf16 v[122:125], v[166:169], v[194:197], v[122:125]
	v_mfma_f32_16x16x32_bf16 v[110:113], v[158:161], v[202:205], v[110:113]
	v_mfma_f32_16x16x32_bf16 v[106:109], v[166:169], v[202:205], v[106:109]
	v_mfma_f32_16x16x32_bf16 v[94:97], v[158:161], v[210:213], v[94:97]
	v_mfma_f32_16x16x32_bf16 v[90:93], v[166:169], v[210:213], v[90:93]
	v_mfma_f32_16x16x32_bf16 v[78:81], v[158:161], v[218:221], v[78:81]
	v_mfma_f32_16x16x32_bf16 v[74:77], v[166:169], v[218:221], v[74:77]
	v_mfma_f32_16x16x32_bf16 v[118:121], v[170:173], v[190:193], v[118:121]
	v_mfma_f32_16x16x32_bf16 v[114:117], v[178:181], v[190:193], v[114:117]
	v_mfma_f32_16x16x32_bf16 v[102:105], v[170:173], v[198:201], v[102:105]
	v_mfma_f32_16x16x32_bf16 v[98:101], v[178:181], v[198:201], v[98:101]
	v_mfma_f32_16x16x32_bf16 v[86:89], v[170:173], v[206:209], v[86:89]
	v_mfma_f32_16x16x32_bf16 v[82:85], v[178:181], v[206:209], v[82:85]
	v_mfma_f32_16x16x32_bf16 v[70:73], v[170:173], v[214:217], v[70:73]
	v_mfma_f32_16x16x32_bf16 v[66:69], v[178:181], v[214:217], v[66:69]
	v_mfma_f32_16x16x32_bf16 v[118:121], v[174:177], v[194:197], v[118:121]
	v_mfma_f32_16x16x32_bf16 v[114:117], v[186:189], v[194:197], v[114:117]
	v_mfma_f32_16x16x32_bf16 v[102:105], v[174:177], v[202:205], v[102:105]
	v_mfma_f32_16x16x32_bf16 v[98:101], v[186:189], v[202:205], v[98:101]
	v_mfma_f32_16x16x32_bf16 v[86:89], v[174:177], v[210:213], v[86:89]
	v_mfma_f32_16x16x32_bf16 v[82:85], v[186:189], v[210:213], v[82:85]
	v_mfma_f32_16x16x32_bf16 v[70:73], v[174:177], v[218:221], v[70:73]
	v_mfma_f32_16x16x32_bf16 v[66:69], v[186:189], v[218:221], v[66:69]
	s_setprio 0
	s_barrier
; #define PG8_STAGE(bufoff, gbase, voff) do { _Pragma("unroll") for (int _i = 0; _i < 2; ++_i) \
;         __builtin_amdgcn_global_load_lds((const unsigned*)((const char*)(gbase) + (voff)[_i]), (LAS unsigned*)(lds + (bufoff) + ldsw + _i * 8192), 16, 0, 0); } while (0)
; #define PG8_LDA(dst, b, h) do { _Pragma("unroll") for (int m = 0; m < 4; ++m) _Pragma("unroll") for (int k = 0; k < 2; ++k) dst[m][k] = *(const LAS bf16x8*)(lds + PG8_SA(b, h) + aoff + m * 2048 + k * 1024); } while (0)
; #define PG8_MMA(ai, bj, At, Bt) do { __builtin_amdgcn_s_setprio(1); _Pragma("unroll") for (int m = 0; m < 4; ++m) _Pragma("unroll") for (int n = 0; n < 2; ++n) _Pragma("unroll") for (int k = 0; k < 2; ++k) \
;         acc[ai][bj][m][n] = __builtin_amdgcn_mfma_f32_16x16x32_bf16(Bt[n][k], At[m][k], acc[ai][bj][m][n], 0, 0, 0); __builtin_amdgcn_s_setprio(0); } while (0)
; #define PG8_WAIT_V(n) asm volatile("s_waitcnt vmcnt(" #n ")" ::: "memory")
; #define PG8_WAIT_L(n) asm volatile("s_waitcnt lgkmcnt(" #n ")" ::: "memory")
; #define PG8_BAR __builtin_amdgcn_s_barrier()
; #define PG8_SCHED __builtin_amdgcn_sched_barrier(0)
; template <class Epi, class Sched>
; DI void gemm_phase(LAS unsigned char* lds, const Gemm g, const Sched& S, const Epi& E) {
;     ...
;         for (int t = 0; t < nt; t += 2) {
;             const bool last = (t == nt - 2);
;             const char* a1 = cA + (size_t)(t + 1) * kstep;
;             const char* a2 = last ? nA : cA + (size_t)(t + 2) * kstep; const char* b2 = last ? nB : cB + (size_t)(t + 2) * kstep;
;             const char* a3 = a2 + kstep; const char* b3 = b2 + kstep;
;     ...
;             PG8_LDA(At, 1, 1); PG8_STAGE(PG8_SB(1, 0), b3, voffB); PG8_STAGE(PG8_SB(1, 1), b3 + hstepB, voffB); PG8_STAGE(PG8_SA(1, 0), a3, voffA);
;             PG8_WAIT_V(8); PG8_WAIT_L(0); PG8_BAR; PG8_MMA(1, 0, At, B0); PG8_MMA(1, 1, At, B1); PG8_BAR; PG8_SCHED;
	s_add_i32 s40, s63, s44
	v_lshl_add_u64 v[182:183], v[182:183], 0, s[16:17]
	s_mov_b32 m0, s40
	ds_read_b128 v[190:193], v156 offset:49152
	ds_read_b128 v[194:197], v156 offset:50176
	ds_read_b128 v[198:201], v156 offset:51200
	ds_read_b128 v[202:205], v156 offset:52224
	ds_read_b128 v[206:209], v156 offset:53248
	ds_read_b128 v[210:213], v156 offset:54272
	ds_read_b128 v[214:217], v156 offset:55296
	ds_read_b128 v[218:221], v156 offset:56320
	global_load_lds_dwordx4 v[182:183], off
	s_add_i32 m0, s40, 0x2000
	s_add_u32 s38, s38, 0xb0080
	v_lshl_add_u64 v[182:183], v[222:223], 0, s[16:17]
	s_addc_u32 s39, s39, 0
	s_add_i32 s40, s64, s44
	global_load_lds_dwordx4 v[182:183], off
	v_lshl_add_u64 v[182:183], s[38:39], 0, v[132:133]
	s_mov_b32 m0, s40
	s_nop 0
	global_load_lds_dwordx4 v[182:183], off
	v_lshl_add_u64 v[182:183], s[38:39], 0, v[136:137]
	s_add_i32 m0, s40, 0x2000
	s_nop 0
	global_load_lds_dwordx4 v[182:183], off
	v_lshl_add_u64 v[182:183], v[224:225], 0, s[16:17]
	s_mov_b32 m0, s50
	s_nop 0
	global_load_lds_dwordx4 v[182:183], off
	v_lshl_add_u64 v[182:183], v[226:227], 0, s[16:17]
	s_mov_b32 m0, s51
	s_nop 0
	global_load_lds_dwordx4 v[182:183], off
	s_waitcnt vmcnt(8)
	s_waitcnt lgkmcnt(0)
	s_barrier
	s_setprio 1
	v_mfma_f32_16x16x32_bf16 v[62:65], v[148:151], v[190:193], v[62:65]
	v_mfma_f32_16x16x32_bf16 v[58:61], v[162:165], v[190:193], v[58:61]
	v_mfma_f32_16x16x32_bf16 v[46:49], v[148:151], v[198:201], v[46:49]
	v_mfma_f32_16x16x32_bf16 v[42:45], v[162:165], v[198:201], v[42:45]
	v_mfma_f32_16x16x32_bf16 v[30:33], v[148:151], v[206:209], v[30:33]
	v_mfma_f32_16x16x32_bf16 v[26:29], v[162:165], v[206:209], v[26:29]
	v_mfma_f32_16x16x32_bf16 v[14:17], v[148:151], v[214:217], v[14:17]
	v_mfma_f32_16x16x32_bf16 v[10:13], v[162:165], v[214:217], v[10:13]
	v_mfma_f32_16x16x32_bf16 v[62:65], v[158:161], v[194:197], v[62:65]
	v_mfma_f32_16x16x32_bf16 v[58:61], v[166:169], v[194:197], v[58:61]
	v_mfma_f32_16x16x32_bf16 v[46:49], v[158:161], v[202:205], v[46:49]
	v_mfma_f32_16x16x32_bf16 v[42:45], v[166:169], v[202:205], v[42:45]
	v_mfma_f32_16x16x32_bf16 v[30:33], v[158:161], v[210:213], v[30:33]
	v_mfma_f32_16x16x32_bf16 v[26:29], v[166:169], v[210:213], v[26:29]
	v_mfma_f32_16x16x32_bf16 v[14:17], v[158:161], v[218:221], v[14:17]
	v_mfma_f32_16x16x32_bf16 v[10:13], v[166:169], v[218:221], v[10:13]
	v_mfma_f32_16x16x32_bf16 v[54:57], v[170:173], v[190:193], v[54:57]
	v_mfma_f32_16x16x32_bf16 v[50:53], v[178:181], v[190:193], v[50:53]
	v_mfma_f32_16x16x32_bf16 v[38:41], v[170:173], v[198:201], v[38:41]
	v_mfma_f32_16x16x32_bf16 v[34:37], v[178:181], v[198:201], v[34:37]
	v_mfma_f32_16x16x32_bf16 v[22:25], v[170:173], v[206:209], v[22:25]
	v_mfma_f32_16x16x32_bf16 v[18:21], v[178:181], v[206:209], v[18:21]
	v_mfma_f32_16x16x32_bf16 v[6:9], v[170:173], v[214:217], v[6:9]
	v_mfma_f32_16x16x32_bf16 v[2:5], v[178:181], v[214:217], v[2:5]
	v_mfma_f32_16x16x32_bf16 v[54:57], v[174:177], v[194:197], v[54:57]
	v_mfma_f32_16x16x32_bf16 v[50:53], v[186:189], v[194:197], v[50:53]
	v_mfma_f32_16x16x32_bf16 v[38:41], v[174:177], v[202:205], v[38:41]
	v_mfma_f32_16x16x32_bf16 v[34:37], v[186:189], v[202:205], v[34:37]
	v_mfma_f32_16x16x32_bf16 v[22:25], v[174:177], v[210:213], v[22:25]
	v_mfma_f32_16x16x32_bf16 v[18:21], v[186:189], v[210:213], v[18:21]
	v_mfma_f32_16x16x32_bf16 v[6:9], v[174:177], v[218:221], v[6:9]
	v_mfma_f32_16x16x32_bf16 v[2:5], v[186:189], v[218:221], v[2:5]
	s_setprio 0
	s_barrier
	s_add_i32 s62, s62, 2
	s_add_u32 s36, s36, 0x100
	s_addc_u32 s37, s37, 0
	s_add_u32 s60, s60, 0x100
	s_addc_u32 s61, s61, 0
	s_cmp_gt_u32 s62, 41
	.p2alignl 6, 3212836864

; #define PG8_STAGE(bufoff, gbase, voff) do { _Pragma("unroll") for (int _i = 0; _i < 2; ++_i) \
;         __builtin_amdgcn_global_load_lds((const unsigned*)((const char*)(gbase) + (voff)[_i]), (LAS unsigned*)(lds + (bufoff) + ldsw + _i * 8192), 16, 0, 0); } while (0)
; #define PG8_LDA(dst, b, h) do { _Pragma("unroll") for (int m = 0; m < 4; ++m) _Pragma("unroll") for (int k = 0; k < 2; ++k) dst[m][k] = *(const LAS bf16x8*)(lds + PG8_SA(b, h) + aoff + m * 2048 + k * 1024); } while (0)
; #define PG8_LDB(dst, b, h) do { _Pragma("unroll") for (int n = 0; n < 2; ++n) _Pragma("unroll") for (int k = 0; k < 2; ++k) dst[n][k] = *(const LAS bf16x8*)(lds + PG8_SB(b, h) + boff + n * 2048 + k * 1024); } while (0)
; #define PG8_MMA(ai, bj, At, Bt) do { __builtin_amdgcn_s_setprio(1); _Pragma("unroll") for (int m = 0; m < 4; ++m) _Pragma("unroll") for (int n = 0; n < 2; ++n) _Pragma("unroll") for (int k = 0; k < 2; ++k) \
;         acc[ai][bj][m][n] = __builtin_amdgcn_mfma_f32_16x16x32_bf16(Bt[n][k], At[m][k], acc[ai][bj][m][n], 0, 0, 0); __builtin_amdgcn_s_setprio(0); } while (0)
; #define PG8_WAIT_V(n) asm volatile("s_waitcnt vmcnt(" #n ")" ::: "memory")
; #define PG8_WAIT_L(n) asm volatile("s_waitcnt lgkmcnt(" #n ")" ::: "memory")
; #define PG8_BAR __builtin_amdgcn_s_barrier()
; #define PG8_SCHED __builtin_amdgcn_sched_barrier(0)
; template <class Epi, class Sched>
; DI void gemm_phase(LAS unsigned char* lds, const Gemm g, const Sched& S, const Epi& E) {
;     ...
;             PG8_LDB(B0, 0, 0); PG8_LDB(B1, 0, 1); PG8_SCHED; PG8_LDA(At, 0, 0); PG8_STAGE(PG8_SA(1, 1), a1 + hstepA, voffA);
;             PG8_WAIT_V(8); PG8_WAIT_L(0); PG8_BAR; PG8_MMA(0, 0, At, B0); PG8_MMA(0, 1, At, B1); PG8_BAR; PG8_SCHED;
;             PG8_LDA(At, 0, 1); PG8_STAGE(PG8_SB(0, 0), b2, voffB); PG8_STAGE(PG8_SB(0, 1), b2 + hstepB, voffB); PG8_STAGE(PG8_SA(0, 0), a2, voffA);
;             PG8_WAIT_V(8); PG8_WAIT_L(0); PG8_BAR; PG8_MMA(1, 0, At, B0); PG8_MMA(1, 1, At, B1); PG8_BAR; PG8_SCHED;
;             PG8_LDB(B0, 1, 0); PG8_LDB(B1, 1, 1); PG8_SCHED; PG8_LDA(At, 1, 0); PG8_STAGE(PG8_SA(0, 1), a2 + hstepA, voffA);
;             PG8_WAIT_V(8); PG8_WAIT_L(0); PG8_BAR; PG8_MMA(0, 0, At, B0); PG8_MMA(0, 1, At, B1); PG8_BAR; PG8_SCHED;
.Lpk2_w2:
	s_mov_b32 s99, 0
	s_waitcnt lgkmcnt(0)
	s_barrier
	s_setprio 1
	v_mfma_f32_16x16x32_bf16 v[62:65], v[138:141], v[218:221], 0
	v_mfma_f32_16x16x32_bf16 v[58:61], v[176:179], v[218:221], 0
	v_mfma_f32_16x16x32_bf16 v[46:49], v[138:141], v[226:229], 0
	v_mfma_f32_16x16x32_bf16 v[42:45], v[176:179], v[226:229], 0
	v_mfma_f32_16x16x32_bf16 v[30:33], v[138:141], v[234:237], 0
	v_mfma_f32_16x16x32_bf16 v[26:29], v[176:179], v[234:237], 0
	v_mfma_f32_16x16x32_bf16 v[14:17], v[138:141], v[242:245], 0
	v_mfma_f32_16x16x32_bf16 v[10:13], v[176:179], v[242:245], 0
	v_mfma_f32_16x16x32_bf16 v[62:65], v[142:145], v[222:225], v[62:65]
	v_mfma_f32_16x16x32_bf16 v[58:61], v[198:201], v[222:225], v[58:61]
	v_mfma_f32_16x16x32_bf16 v[46:49], v[142:145], v[230:233], v[46:49]
	v_mfma_f32_16x16x32_bf16 v[42:45], v[198:201], v[230:233], v[42:45]
	v_mfma_f32_16x16x32_bf16 v[30:33], v[142:145], v[238:241], v[30:33]
	v_mfma_f32_16x16x32_bf16 v[26:29], v[198:201], v[238:241], v[26:29]
	v_mfma_f32_16x16x32_bf16 v[14:17], v[142:145], v[246:249], v[14:17]
	v_mfma_f32_16x16x32_bf16 v[10:13], v[198:201], v[246:249], v[10:13]
	v_mfma_f32_16x16x32_bf16 v[54:57], v[202:205], v[218:221], 0
	v_mfma_f32_16x16x32_bf16 v[50:53], v[210:213], v[218:221], 0
	v_mfma_f32_16x16x32_bf16 v[38:41], v[202:205], v[226:229], 0
	v_mfma_f32_16x16x32_bf16 v[34:37], v[210:213], v[226:229], 0
	v_mfma_f32_16x16x32_bf16 v[22:25], v[202:205], v[234:237], 0
	v_mfma_f32_16x16x32_bf16 v[18:21], v[210:213], v[234:237], 0
	v_mfma_f32_16x16x32_bf16 v[6:9], v[202:205], v[242:245], 0
	v_mfma_f32_16x16x32_bf16 v[2:5], v[210:213], v[242:245], 0
	v_mfma_f32_16x16x32_bf16 v[54:57], v[206:209], v[222:225], v[54:57]
	v_mfma_f32_16x16x32_bf16 v[50:53], v[214:217], v[222:225], v[50:53]
	v_mfma_f32_16x16x32_bf16 v[38:41], v[206:209], v[230:233], v[38:41]
	v_mfma_f32_16x16x32_bf16 v[34:37], v[214:217], v[230:233], v[34:37]
	v_mfma_f32_16x16x32_bf16 v[22:25], v[206:209], v[238:241], v[22:25]
	v_mfma_f32_16x16x32_bf16 v[18:21], v[214:217], v[238:241], v[18:21]
	v_mfma_f32_16x16x32_bf16 v[6:9], v[206:209], v[246:249], v[6:9]
	v_mfma_f32_16x16x32_bf16 v[2:5], v[214:217], v[246:249], v[2:5]
	s_setprio 0
	s_barrier
	s_add_i32 s70, 0, 0x18000
	v_add_u32_e32 v156, s70, v159
	s_add_i32 s71, 0, 0x1c000
	ds_read_b128 v[138:141], v156
	ds_read_b128 v[142:145], v156 offset:1024
	ds_read_b128 v[176:179], v156 offset:2048
	ds_read_b128 v[198:201], v156 offset:3072
	v_add_u32_e32 v156, s71, v159
	ds_read_b128 v[202:205], v156
	ds_read_b128 v[206:209], v156 offset:1024
	ds_read_b128 v[210:213], v156 offset:2048
	ds_read_b128 v[214:217], v156 offset:3072
	s_add_u32 s66, s66, 0x40000
	s_addc_u32 s67, s67, 0
	s_mov_b32 m0, s81
	v_lshl_add_u64 v[254:255], s[66:67], 0, v[148:149]
	ds_read_b128 v[218:221], v186 offset:32768
	ds_read_b128 v[222:225], v186 offset:33792
	ds_read_b128 v[226:229], v186 offset:34816
	ds_read_b128 v[230:233], v186 offset:35840
	ds_read_b128 v[234:237], v186 offset:36864
	ds_read_b128 v[238:241], v186 offset:37888
	ds_read_b128 v[242:245], v186 offset:38912
	ds_read_b128 v[246:249], v186 offset:39936
	global_load_lds_dwordx4 v[254:255], off
	v_lshl_add_u64 v[254:255], s[66:67], 0, v[152:153]
	s_mov_b32 m0, s82
	s_nop 0
	global_load_lds_dwordx4 v[254:255], off
	s_waitcnt vmcnt(8)
	s_waitcnt lgkmcnt(0)
	s_barrier
	s_setprio 1
	v_mfma_f32_16x16x32_bf16 v[126:129], v[138:141], v[218:221], v[126:129]
	v_mfma_f32_16x16x32_bf16 v[122:125], v[176:179], v[218:221], v[122:125]
	v_mfma_f32_16x16x32_bf16 v[110:113], v[138:141], v[226:229], v[110:113]
	v_mfma_f32_16x16x32_bf16 v[106:109], v[176:179], v[226:229], v[106:109]
	v_mfma_f32_16x16x32_bf16 v[94:97], v[138:141], v[234:237], v[94:97]
	v_mfma_f32_16x16x32_bf16 v[90:93], v[176:179], v[234:237], v[90:93]
	v_mfma_f32_16x16x32_bf16 v[78:81], v[138:141], v[242:245], v[78:81]
	v_mfma_f32_16x16x32_bf16 v[74:77], v[176:179], v[242:245], v[74:77]
	v_mfma_f32_16x16x32_bf16 v[126:129], v[142:145], v[222:225], v[126:129]
	v_mfma_f32_16x16x32_bf16 v[122:125], v[198:201], v[222:225], v[122:125]
	v_mfma_f32_16x16x32_bf16 v[110:113], v[142:145], v[230:233], v[110:113]
	v_mfma_f32_16x16x32_bf16 v[106:109], v[198:201], v[230:233], v[106:109]
	v_mfma_f32_16x16x32_bf16 v[94:97], v[142:145], v[238:241], v[94:97]
	v_mfma_f32_16x16x32_bf16 v[90:93], v[198:201], v[238:241], v[90:93]
	v_mfma_f32_16x16x32_bf16 v[78:81], v[142:145], v[246:249], v[78:81]
	v_mfma_f32_16x16x32_bf16 v[74:77], v[198:201], v[246:249], v[74:77]
	v_mfma_f32_16x16x32_bf16 v[118:121], v[202:205], v[218:221], v[118:121]
	v_mfma_f32_16x16x32_bf16 v[114:117], v[210:213], v[218:221], v[114:117]
	v_mfma_f32_16x16x32_bf16 v[102:105], v[202:205], v[226:229], v[102:105]
	v_mfma_f32_16x16x32_bf16 v[98:101], v[210:213], v[226:229], v[98:101]
	v_mfma_f32_16x16x32_bf16 v[86:89], v[202:205], v[234:237], v[86:89]
	v_mfma_f32_16x16x32_bf16 v[82:85], v[210:213], v[234:237], v[82:85]
	v_mfma_f32_16x16x32_bf16 v[70:73], v[202:205], v[242:245], v[70:73]
	v_mfma_f32_16x16x32_bf16 v[66:69], v[210:213], v[242:245], v[66:69]
	v_mfma_f32_16x16x32_bf16 v[118:121], v[206:209], v[222:225], v[118:121]
	v_mfma_f32_16x16x32_bf16 v[114:117], v[214:217], v[222:225], v[114:117]
	v_mfma_f32_16x16x32_bf16 v[102:105], v[206:209], v[230:233], v[102:105]
	v_mfma_f32_16x16x32_bf16 v[98:101], v[214:217], v[230:233], v[98:101]
	v_mfma_f32_16x16x32_bf16 v[86:89], v[206:209], v[238:241], v[86:89]
	v_mfma_f32_16x16x32_bf16 v[82:85], v[214:217], v[238:241], v[82:85]
	v_mfma_f32_16x16x32_bf16 v[70:73], v[206:209], v[246:249], v[70:73]
	v_mfma_f32_16x16x32_bf16 v[66:69], v[214:217], v[246:249], v[66:69]
	s_setprio 0
	s_barrier
; #define PG8_STAGE(bufoff, gbase, voff) do { _Pragma("unroll") for (int _i = 0; _i < 2; ++_i) \
;         __builtin_amdgcn_global_load_lds((const unsigned*)((const char*)(gbase) + (voff)[_i]), (LAS unsigned*)(lds + (bufoff) + ldsw + _i * 8192), 16, 0, 0); } while (0)
; #define PG8_LDA(dst, b, h) do { _Pragma("unroll") for (int m = 0; m < 4; ++m) _Pragma("unroll") for (int k = 0; k < 2; ++k) dst[m][k] = *(const LAS bf16x8*)(lds + PG8_SA(b, h) + aoff + m * 2048 + k * 1024); } while (0)
; #define PG8_MMA(ai, bj, At, Bt) do { __builtin_amdgcn_s_setprio(1); _Pragma("unroll") for (int m = 0; m < 4; ++m) _Pragma("unroll") for (int n = 0; n < 2; ++n) _Pragma("unroll") for (int k = 0; k < 2; ++k) \
;         acc[ai][bj][m][n] = __builtin_amdgcn_mfma_f32_16x16x32_bf16(Bt[n][k], At[m][k], acc[ai][bj][m][n], 0, 0, 0); __builtin_amdgcn_s_setprio(0); } while (0)
; #define PG8_WAIT_V(n) asm volatile("s_waitcnt vmcnt(" #n ")" ::: "memory")
; #define PG8_WAIT_L(n) asm volatile("s_waitcnt lgkmcnt(" #n ")" ::: "memory")
; #define PG8_BAR __builtin_amdgcn_s_barrier()
; #define PG8_SCHED __builtin_amdgcn_sched_barrier(0)
; template <class Epi, class Sched>
; DI void gemm_phase(LAS unsigned char* lds, const Gemm g, const Sched& S, const Epi& E) {
;     ...
;         for (int t = 0; t < nt; t += 2) {
;             const bool last = (t == nt - 2);
;             const char* a1 = cA + (size_t)(t + 1) * kstep;
;             const char* a2 = last ? nA : cA + (size_t)(t + 2) * kstep; const char* b2 = last ? nB : cB + (size_t)(t + 2) * kstep;
;             const char* a3 = a2 + kstep; const char* b3 = b2 + kstep;
;     ...
;             PG8_LDA(At, 1, 1); PG8_STAGE(PG8_SB(1, 0), b3, voffB); PG8_STAGE(PG8_SB(1, 1), b3 + hstepB, voffB); PG8_STAGE(PG8_SA(1, 0), a3, voffA);
;             PG8_WAIT_V(8); PG8_WAIT_L(0); PG8_BAR; PG8_MMA(1, 0, At, B0); PG8_MMA(1, 1, At, B1); PG8_BAR; PG8_SCHED;
	s_add_i32 s66, s70, s78
	v_lshl_add_u64 v[172:173], v[172:173], 0, s[50:51]
	s_mov_b32 m0, s66
	ds_read_b128 v[218:221], v186 offset:49152
	ds_read_b128 v[222:225], v186 offset:50176
	ds_read_b128 v[226:229], v186 offset:51200
	ds_read_b128 v[230:233], v186 offset:52224
	ds_read_b128 v[234:237], v186 offset:53248
	ds_read_b128 v[238:241], v186 offset:54272
	ds_read_b128 v[242:245], v186 offset:55296
	ds_read_b128 v[246:249], v186 offset:56320
	global_load_lds_dwordx4 v[172:173], off
	s_add_i32 m0, s66, 0x2000
	s_add_u32 s64, s64, 0x40080
	v_lshl_add_u64 v[172:173], v[180:181], 0, s[50:51]
	s_addc_u32 s65, s65, 0
	s_add_i32 s66, s71, s78
	global_load_lds_dwordx4 v[172:173], off
	v_lshl_add_u64 v[172:173], s[64:65], 0, v[150:151]
	s_mov_b32 m0, s66
	s_nop 0
	global_load_lds_dwordx4 v[172:173], off
	v_lshl_add_u64 v[172:173], s[64:65], 0, v[154:155]
	s_add_i32 m0, s66, 0x2000
	s_nop 0
	global_load_lds_dwordx4 v[172:173], off
	v_lshl_add_u64 v[172:173], v[250:251], 0, s[50:51]
	s_mov_b32 m0, s86
	s_nop 0
	global_load_lds_dwordx4 v[172:173], off
	v_lshl_add_u64 v[172:173], v[252:253], 0, s[50:51]
	s_mov_b32 m0, s87
	s_nop 0
	global_load_lds_dwordx4 v[172:173], off
	s_waitcnt vmcnt(8)
	s_waitcnt lgkmcnt(0)
	s_barrier
	s_setprio 1
	v_mfma_f32_16x16x32_bf16 v[62:65], v[138:141], v[218:221], v[62:65]
	v_mfma_f32_16x16x32_bf16 v[58:61], v[176:179], v[218:221], v[58:61]
	v_mfma_f32_16x16x32_bf16 v[46:49], v[138:141], v[226:229], v[46:49]
	v_mfma_f32_16x16x32_bf16 v[42:45], v[176:179], v[226:229], v[42:45]
	v_mfma_f32_16x16x32_bf16 v[30:33], v[138:141], v[234:237], v[30:33]
	v_mfma_f32_16x16x32_bf16 v[26:29], v[176:179], v[234:237], v[26:29]
	v_mfma_f32_16x16x32_bf16 v[14:17], v[138:141], v[242:245], v[14:17]
	v_mfma_f32_16x16x32_bf16 v[10:13], v[176:179], v[242:245], v[10:13]
	v_mfma_f32_16x16x32_bf16 v[62:65], v[142:145], v[222:225], v[62:65]
	v_mfma_f32_16x16x32_bf16 v[58:61], v[198:201], v[222:225], v[58:61]
	v_mfma_f32_16x16x32_bf16 v[46:49], v[142:145], v[230:233], v[46:49]
	v_mfma_f32_16x16x32_bf16 v[42:45], v[198:201], v[230:233], v[42:45]
	v_mfma_f32_16x16x32_bf16 v[30:33], v[142:145], v[238:241], v[30:33]
	v_mfma_f32_16x16x32_bf16 v[26:29], v[198:201], v[238:241], v[26:29]
	v_mfma_f32_16x16x32_bf16 v[14:17], v[142:145], v[246:249], v[14:17]
	v_mfma_f32_16x16x32_bf16 v[10:13], v[198:201], v[246:249], v[10:13]
	v_mfma_f32_16x16x32_bf16 v[54:57], v[202:205], v[218:221], v[54:57]
	v_mfma_f32_16x16x32_bf16 v[50:53], v[210:213], v[218:221], v[50:53]
	v_mfma_f32_16x16x32_bf16 v[38:41], v[202:205], v[226:229], v[38:41]
	v_mfma_f32_16x16x32_bf16 v[34:37], v[210:213], v[226:229], v[34:37]
	v_mfma_f32_16x16x32_bf16 v[22:25], v[202:205], v[234:237], v[22:25]
	v_mfma_f32_16x16x32_bf16 v[18:21], v[210:213], v[234:237], v[18:21]
	v_mfma_f32_16x16x32_bf16 v[6:9], v[202:205], v[242:245], v[6:9]
	v_mfma_f32_16x16x32_bf16 v[2:5], v[210:213], v[242:245], v[2:5]
	v_mfma_f32_16x16x32_bf16 v[54:57], v[206:209], v[222:225], v[54:57]
	v_mfma_f32_16x16x32_bf16 v[50:53], v[214:217], v[222:225], v[50:53]
	v_mfma_f32_16x16x32_bf16 v[38:41], v[206:209], v[230:233], v[38:41]
	v_mfma_f32_16x16x32_bf16 v[34:37], v[214:217], v[230:233], v[34:37]
	v_mfma_f32_16x16x32_bf16 v[22:25], v[206:209], v[238:241], v[22:25]
	v_mfma_f32_16x16x32_bf16 v[18:21], v[214:217], v[238:241], v[18:21]
	v_mfma_f32_16x16x32_bf16 v[6:9], v[206:209], v[246:249], v[6:9]
	v_mfma_f32_16x16x32_bf16 v[2:5], v[214:217], v[246:249], v[2:5]
	s_setprio 0
	s_barrier
	s_add_i32 s69, s69, 2
	s_add_u32 s10, s10, 0x100
	s_addc_u32 s11, s11, 0
	s_add_u32 s59, s59, 0x100
	s_addc_u32 s68, s68, 0
	s_cmp_gt_u32 s69, 13
	.p2alignl 6, 3212836864

; #define PG8_STAGE(bufoff, gbase, voff) do { _Pragma("unroll") for (int _i = 0; _i < 2; ++_i) \
;         __builtin_amdgcn_global_load_lds((const unsigned*)((const char*)(gbase) + (voff)[_i]), (LAS unsigned*)(lds + (bufoff) + ldsw + _i * 8192), 16, 0, 0); } while (0)
; #define PG8_LDA(dst, b, h) do { _Pragma("unroll") for (int m = 0; m < 4; ++m) _Pragma("unroll") for (int k = 0; k < 2; ++k) dst[m][k] = *(const LAS bf16x8*)(lds + PG8_SA(b, h) + aoff + m * 2048 + k * 1024); } while (0)
; #define PG8_LDB(dst, b, h) do { _Pragma("unroll") for (int n = 0; n < 2; ++n) _Pragma("unroll") for (int k = 0; k < 2; ++k) dst[n][k] = *(const LAS bf16x8*)(lds + PG8_SB(b, h) + boff + n * 2048 + k * 1024); } while (0)
; #define PG8_MMA(ai, bj, At, Bt) do { __builtin_amdgcn_s_setprio(1); _Pragma("unroll") for (int m = 0; m < 4; ++m) _Pragma("unroll") for (int n = 0; n < 2; ++n) _Pragma("unroll") for (int k = 0; k < 2; ++k) \
;         acc[ai][bj][m][n] = __builtin_amdgcn_mfma_f32_16x16x32_bf16(Bt[n][k], At[m][k], acc[ai][bj][m][n], 0, 0, 0); __builtin_amdgcn_s_setprio(0); } while (0)
; #define PG8_WAIT_V(n) asm volatile("s_waitcnt vmcnt(" #n ")" ::: "memory")
; #define PG8_WAIT_L(n) asm volatile("s_waitcnt lgkmcnt(" #n ")" ::: "memory")
; #define PG8_BAR __builtin_amdgcn_s_barrier()
; #define PG8_SCHED __builtin_amdgcn_sched_barrier(0)
; template <class Epi, class Sched>
; DI void gemm_phase(LAS unsigned char* lds, const Gemm g, const Sched& S, const Epi& E) {
;     ...
;             PG8_LDB(B0, 0, 0); PG8_LDB(B1, 0, 1); PG8_SCHED; PG8_LDA(At, 0, 0); PG8_STAGE(PG8_SA(1, 1), a1 + hstepA, voffA);
;             PG8_WAIT_V(8); PG8_WAIT_L(0); PG8_BAR; PG8_MMA(0, 0, At, B0); PG8_MMA(0, 1, At, B1); PG8_BAR; PG8_SCHED;
;             PG8_LDA(At, 0, 1); PG8_STAGE(PG8_SB(0, 0), b2, voffB); PG8_STAGE(PG8_SB(0, 1), b2 + hstepB, voffB); PG8_STAGE(PG8_SA(0, 0), a2, voffA);
;             PG8_WAIT_V(8); PG8_WAIT_L(0); PG8_BAR; PG8_MMA(1, 0, At, B0); PG8_MMA(1, 1, At, B1); PG8_BAR; PG8_SCHED;
;             PG8_LDB(B0, 1, 0); PG8_LDB(B1, 1, 1); PG8_SCHED; PG8_LDA(At, 1, 0); PG8_STAGE(PG8_SA(0, 1), a2 + hstepA, voffA);
;             PG8_WAIT_V(8); PG8_WAIT_L(0); PG8_BAR; PG8_MMA(0, 0, At, B0); PG8_MMA(0, 1, At, B1); PG8_BAR; PG8_SCHED;
.Lpk3_w2:
	s_mov_b32 s99, 0
	s_waitcnt lgkmcnt(0)
	s_barrier
	s_setprio 1
	v_mfma_f32_16x16x32_bf16 v[62:65], v[146:149], v[186:189], v[62:65]
	v_mfma_f32_16x16x32_bf16 v[58:61], v[154:157], v[186:189], v[58:61]
	v_mfma_f32_16x16x32_bf16 v[54:57], v[146:149], v[194:197], v[54:57]
	v_mfma_f32_16x16x32_bf16 v[50:53], v[154:157], v[194:197], v[50:53]
	v_mfma_f32_16x16x32_bf16 v[46:49], v[146:149], v[202:205], v[46:49]
	v_mfma_f32_16x16x32_bf16 v[42:45], v[154:157], v[202:205], v[42:45]
	v_mfma_f32_16x16x32_bf16 v[38:41], v[146:149], v[210:213], v[38:41]
	v_mfma_f32_16x16x32_bf16 v[34:37], v[154:157], v[210:213], v[34:37]
	v_mfma_f32_16x16x32_bf16 v[62:65], v[150:153], v[190:193], v[62:65]
	v_mfma_f32_16x16x32_bf16 v[58:61], v[158:161], v[190:193], v[58:61]
	v_mfma_f32_16x16x32_bf16 v[54:57], v[150:153], v[198:201], v[54:57]
	v_mfma_f32_16x16x32_bf16 v[50:53], v[158:161], v[198:201], v[50:53]
	v_mfma_f32_16x16x32_bf16 v[46:49], v[150:153], v[206:209], v[46:49]
	v_mfma_f32_16x16x32_bf16 v[42:45], v[158:161], v[206:209], v[42:45]
	v_mfma_f32_16x16x32_bf16 v[38:41], v[150:153], v[214:217], v[38:41]
	v_mfma_f32_16x16x32_bf16 v[34:37], v[158:161], v[214:217], v[34:37]
	v_mfma_f32_16x16x32_bf16 v[30:33], v[168:171], v[186:189], v[30:33]
	v_mfma_f32_16x16x32_bf16 v[26:29], v[176:179], v[186:189], v[26:29]
	v_mfma_f32_16x16x32_bf16 v[22:25], v[168:171], v[194:197], v[22:25]
	v_mfma_f32_16x16x32_bf16 v[18:21], v[176:179], v[194:197], v[18:21]
	v_mfma_f32_16x16x32_bf16 v[14:17], v[168:171], v[202:205], v[14:17]
	v_mfma_f32_16x16x32_bf16 v[10:13], v[176:179], v[202:205], v[10:13]
	v_mfma_f32_16x16x32_bf16 v[6:9], v[168:171], v[210:213], v[6:9]
	v_mfma_f32_16x16x32_bf16 v[2:5], v[176:179], v[210:213], v[2:5]
	v_mfma_f32_16x16x32_bf16 v[30:33], v[172:175], v[190:193], v[30:33]
	v_mfma_f32_16x16x32_bf16 v[26:29], v[180:183], v[190:193], v[26:29]
	v_mfma_f32_16x16x32_bf16 v[22:25], v[172:175], v[198:201], v[22:25]
	v_mfma_f32_16x16x32_bf16 v[18:21], v[180:183], v[198:201], v[18:21]
	v_mfma_f32_16x16x32_bf16 v[14:17], v[172:175], v[206:209], v[14:17]
	v_mfma_f32_16x16x32_bf16 v[10:13], v[180:183], v[206:209], v[10:13]
	v_mfma_f32_16x16x32_bf16 v[6:9], v[172:175], v[214:217], v[6:9]
	v_mfma_f32_16x16x32_bf16 v[2:5], v[180:183], v[214:217], v[2:5]
	s_setprio 0
	s_barrier
	s_add_i32 s73, 0, 0x18000
	s_add_i32 s74, 0, 0x1c000
	v_add_u32_e32 v158, s73, v162
	v_add_u32_e32 v180, s74, v162
	ds_read_b128 v[146:149], v158
	ds_read_b128 v[150:153], v158 offset:1024
	ds_read_b128 v[154:157], v158 offset:2048
	ds_read_b128 v[158:161], v158 offset:3072
	ds_read_b128 v[168:171], v180
	ds_read_b128 v[172:175], v180 offset:1024
	ds_read_b128 v[176:179], v180 offset:2048
	ds_read_b128 v[180:183], v180 offset:3072
	s_add_u32 s48, s48, 0x20000
	s_addc_u32 s49, s49, 0
	s_mov_b32 m0, s55
	v_lshl_add_u64 v[226:227], s[48:49], 0, v[130:131]
	ds_read_b128 v[186:189], v167 offset:32768
	ds_read_b128 v[190:193], v167 offset:33792
	ds_read_b128 v[194:197], v167 offset:34816
	ds_read_b128 v[198:201], v167 offset:35840
	ds_read_b128 v[202:205], v167 offset:36864
	ds_read_b128 v[206:209], v167 offset:37888
	ds_read_b128 v[210:213], v167 offset:38912
	ds_read_b128 v[214:217], v167 offset:39936
	global_load_lds_dwordx4 v[226:227], off
	v_lshl_add_u64 v[226:227], s[48:49], 0, v[134:135]
	s_mov_b32 m0, s56
	s_nop 0
	global_load_lds_dwordx4 v[226:227], off
	s_waitcnt vmcnt(8)
	s_waitcnt lgkmcnt(0)
	s_barrier
	s_setprio 1
	v_mfma_f32_16x16x32_bf16 v[126:129], v[146:149], v[186:189], v[126:129]
	v_mfma_f32_16x16x32_bf16 v[122:125], v[154:157], v[186:189], v[122:125]
	v_mfma_f32_16x16x32_bf16 v[118:121], v[146:149], v[194:197], v[118:121]
	v_mfma_f32_16x16x32_bf16 v[114:117], v[154:157], v[194:197], v[114:117]
	v_mfma_f32_16x16x32_bf16 v[110:113], v[146:149], v[202:205], v[110:113]
	v_mfma_f32_16x16x32_bf16 v[106:109], v[154:157], v[202:205], v[106:109]
	v_mfma_f32_16x16x32_bf16 v[102:105], v[146:149], v[210:213], v[102:105]
	v_mfma_f32_16x16x32_bf16 v[98:101], v[154:157], v[210:213], v[98:101]
	v_mfma_f32_16x16x32_bf16 v[126:129], v[150:153], v[190:193], v[126:129]
	v_mfma_f32_16x16x32_bf16 v[122:125], v[158:161], v[190:193], v[122:125]
	v_mfma_f32_16x16x32_bf16 v[118:121], v[150:153], v[198:201], v[118:121]
	v_mfma_f32_16x16x32_bf16 v[114:117], v[158:161], v[198:201], v[114:117]
	v_mfma_f32_16x16x32_bf16 v[110:113], v[150:153], v[206:209], v[110:113]
	v_mfma_f32_16x16x32_bf16 v[106:109], v[158:161], v[206:209], v[106:109]
	v_mfma_f32_16x16x32_bf16 v[102:105], v[150:153], v[214:217], v[102:105]
	v_mfma_f32_16x16x32_bf16 v[98:101], v[158:161], v[214:217], v[98:101]
	v_mfma_f32_16x16x32_bf16 v[94:97], v[168:171], v[186:189], v[94:97]
	v_mfma_f32_16x16x32_bf16 v[90:93], v[176:179], v[186:189], v[90:93]
	v_mfma_f32_16x16x32_bf16 v[86:89], v[168:171], v[194:197], v[86:89]
	v_mfma_f32_16x16x32_bf16 v[82:85], v[176:179], v[194:197], v[82:85]
	v_mfma_f32_16x16x32_bf16 v[78:81], v[168:171], v[202:205], v[78:81]
	v_mfma_f32_16x16x32_bf16 v[74:77], v[176:179], v[202:205], v[74:77]
	v_mfma_f32_16x16x32_bf16 v[70:73], v[168:171], v[210:213], v[70:73]
	v_mfma_f32_16x16x32_bf16 v[66:69], v[176:179], v[210:213], v[66:69]
	v_mfma_f32_16x16x32_bf16 v[94:97], v[172:175], v[190:193], v[94:97]
	v_mfma_f32_16x16x32_bf16 v[90:93], v[180:183], v[190:193], v[90:93]
	v_mfma_f32_16x16x32_bf16 v[86:89], v[172:175], v[198:201], v[86:89]
	v_mfma_f32_16x16x32_bf16 v[82:85], v[180:183], v[198:201], v[82:85]
	v_mfma_f32_16x16x32_bf16 v[78:81], v[172:175], v[206:209], v[78:81]
	v_mfma_f32_16x16x32_bf16 v[74:77], v[180:183], v[206:209], v[74:77]
	v_mfma_f32_16x16x32_bf16 v[70:73], v[172:175], v[214:217], v[70:73]
	v_mfma_f32_16x16x32_bf16 v[66:69], v[180:183], v[214:217], v[66:69]
	s_setprio 0
	s_barrier
; #define PG8_STAGE(bufoff, gbase, voff) do { _Pragma("unroll") for (int _i = 0; _i < 2; ++_i) \
;         __builtin_amdgcn_global_load_lds((const unsigned*)((const char*)(gbase) + (voff)[_i]), (LAS unsigned*)(lds + (bufoff) + ldsw + _i * 8192), 16, 0, 0); } while (0)
; #define PG8_LDA(dst, b, h) do { _Pragma("unroll") for (int m = 0; m < 4; ++m) _Pragma("unroll") for (int k = 0; k < 2; ++k) dst[m][k] = *(const LAS bf16x8*)(lds + PG8_SA(b, h) + aoff + m * 2048 + k * 1024); } while (0)
; #define PG8_MMA(ai, bj, At, Bt) do { __builtin_amdgcn_s_setprio(1); _Pragma("unroll") for (int m = 0; m < 4; ++m) _Pragma("unroll") for (int n = 0; n < 2; ++n) _Pragma("unroll") for (int k = 0; k < 2; ++k) \
;         acc[ai][bj][m][n] = __builtin_amdgcn_mfma_f32_16x16x32_bf16(Bt[n][k], At[m][k], acc[ai][bj][m][n], 0, 0, 0); __builtin_amdgcn_s_setprio(0); } while (0)
; #define PG8_WAIT_V(n) asm volatile("s_waitcnt vmcnt(" #n ")" ::: "memory")
; #define PG8_WAIT_L(n) asm volatile("s_waitcnt lgkmcnt(" #n ")" ::: "memory")
; #define PG8_BAR __builtin_amdgcn_s_barrier()
; #define PG8_SCHED __builtin_amdgcn_sched_barrier(0)
; template <class Epi, class Sched>
; DI void gemm_phase(LAS unsigned char* lds, const Gemm g, const Sched& S, const Epi& E) {
;     ...
;         for (int t = 0; t < nt; t += 2) {
;             const bool last = (t == nt - 2);
;             const char* a1 = cA + (size_t)(t + 1) * kstep;
;             const char* a2 = last ? nA : cA + (size_t)(t + 2) * kstep; const char* b2 = last ? nB : cB + (size_t)(t + 2) * kstep;
;             const char* a3 = a2 + kstep; const char* b3 = b2 + kstep;
;     ...
;             PG8_LDA(At, 1, 1); PG8_STAGE(PG8_SB(1, 0), b3, voffB); PG8_STAGE(PG8_SB(1, 1), b3 + hstepB, voffB); PG8_STAGE(PG8_SA(1, 0), a3, voffA);
;             PG8_WAIT_V(8); PG8_WAIT_L(0); PG8_BAR; PG8_MMA(1, 0, At, B0); PG8_MMA(1, 1, At, B1); PG8_BAR; PG8_SCHED;
	s_add_i32 s48, s73, s52
	v_lshl_add_u64 v[218:219], v[218:219], 0, s[20:21]
	s_mov_b32 m0, s48
	ds_read_b128 v[186:189], v167 offset:49152
	ds_read_b128 v[190:193], v167 offset:50176
	ds_read_b128 v[194:197], v167 offset:51200
	ds_read_b128 v[198:201], v167 offset:52224
	ds_read_b128 v[202:205], v167 offset:53248
	ds_read_b128 v[206:209], v167 offset:54272
	ds_read_b128 v[210:213], v167 offset:55296
	ds_read_b128 v[214:217], v167 offset:56320
	global_load_lds_dwordx4 v[218:219], off
	s_add_i32 m0, s48, 0x2000
	s_add_u32 s46, s46, 0x20080
	v_lshl_add_u64 v[218:219], v[220:221], 0, s[20:21]
	s_addc_u32 s47, s47, 0
	s_add_i32 s48, s74, s52
	global_load_lds_dwordx4 v[218:219], off
	v_lshl_add_u64 v[218:219], s[46:47], 0, v[132:133]
	s_mov_b32 m0, s48
	s_nop 0
	global_load_lds_dwordx4 v[218:219], off
	v_lshl_add_u64 v[218:219], s[46:47], 0, v[136:137]
	s_add_i32 m0, s48, 0x2000
	s_nop 0
	global_load_lds_dwordx4 v[218:219], off
	v_lshl_add_u64 v[218:219], v[222:223], 0, s[20:21]
	s_mov_b32 m0, s61
	s_nop 0
	global_load_lds_dwordx4 v[218:219], off
	v_lshl_add_u64 v[218:219], v[224:225], 0, s[20:21]
	s_mov_b32 m0, s62
	s_nop 0
	global_load_lds_dwordx4 v[218:219], off
	s_waitcnt vmcnt(8)
	s_waitcnt lgkmcnt(0)
	s_barrier
	s_setprio 1
	v_mfma_f32_16x16x32_bf16 v[62:65], v[146:149], v[186:189], v[62:65]
	v_mfma_f32_16x16x32_bf16 v[58:61], v[154:157], v[186:189], v[58:61]
	v_mfma_f32_16x16x32_bf16 v[54:57], v[146:149], v[194:197], v[54:57]
	v_mfma_f32_16x16x32_bf16 v[50:53], v[154:157], v[194:197], v[50:53]
	v_mfma_f32_16x16x32_bf16 v[46:49], v[146:149], v[202:205], v[46:49]
	v_mfma_f32_16x16x32_bf16 v[42:45], v[154:157], v[202:205], v[42:45]
	v_mfma_f32_16x16x32_bf16 v[38:41], v[146:149], v[210:213], v[38:41]
	v_mfma_f32_16x16x32_bf16 v[34:37], v[154:157], v[210:213], v[34:37]
	v_mfma_f32_16x16x32_bf16 v[62:65], v[150:153], v[190:193], v[62:65]
	v_mfma_f32_16x16x32_bf16 v[58:61], v[158:161], v[190:193], v[58:61]
	v_mfma_f32_16x16x32_bf16 v[54:57], v[150:153], v[198:201], v[54:57]
	v_mfma_f32_16x16x32_bf16 v[50:53], v[158:161], v[198:201], v[50:53]
	v_mfma_f32_16x16x32_bf16 v[46:49], v[150:153], v[206:209], v[46:49]
	v_mfma_f32_16x16x32_bf16 v[42:45], v[158:161], v[206:209], v[42:45]
	v_mfma_f32_16x16x32_bf16 v[38:41], v[150:153], v[214:217], v[38:41]
	v_mfma_f32_16x16x32_bf16 v[34:37], v[158:161], v[214:217], v[34:37]
	v_mfma_f32_16x16x32_bf16 v[30:33], v[168:171], v[186:189], v[30:33]
	v_mfma_f32_16x16x32_bf16 v[26:29], v[176:179], v[186:189], v[26:29]
	v_mfma_f32_16x16x32_bf16 v[22:25], v[168:171], v[194:197], v[22:25]
	v_mfma_f32_16x16x32_bf16 v[18:21], v[176:179], v[194:197], v[18:21]
	v_mfma_f32_16x16x32_bf16 v[14:17], v[168:171], v[202:205], v[14:17]
	v_mfma_f32_16x16x32_bf16 v[10:13], v[176:179], v[202:205], v[10:13]
	v_mfma_f32_16x16x32_bf16 v[6:9], v[168:171], v[210:213], v[6:9]
	v_mfma_f32_16x16x32_bf16 v[2:5], v[176:179], v[210:213], v[2:5]
	v_mfma_f32_16x16x32_bf16 v[30:33], v[172:175], v[190:193], v[30:33]
	v_mfma_f32_16x16x32_bf16 v[26:29], v[180:183], v[190:193], v[26:29]
	v_mfma_f32_16x16x32_bf16 v[22:25], v[172:175], v[198:201], v[22:25]
	v_mfma_f32_16x16x32_bf16 v[18:21], v[180:183], v[198:201], v[18:21]
	v_mfma_f32_16x16x32_bf16 v[14:17], v[172:175], v[206:209], v[14:17]
	v_mfma_f32_16x16x32_bf16 v[10:13], v[180:183], v[206:209], v[10:13]
	v_mfma_f32_16x16x32_bf16 v[6:9], v[172:175], v[214:217], v[6:9]
	v_mfma_f32_16x16x32_bf16 v[2:5], v[180:183], v[214:217], v[2:5]
	s_setprio 0
	s_barrier
	s_add_i32 s72, s72, 2
	s_add_u32 s44, s44, 0x100
	s_addc_u32 s45, s45, 0
	s_add_u32 s70, s70, 0x100
	s_addc_u32 s71, s71, 0
	s_cmp_gt_u32 s72, 5
	.p2alignl 6, 3212836864

; #define PG8_STAGE(bufoff, gbase, voff) do { _Pragma("unroll") for (int _i = 0; _i < 2; ++_i) \
;         __builtin_amdgcn_global_load_lds((const unsigned*)((const char*)(gbase) + (voff)[_i]), (LAS unsigned*)(lds + (bufoff) + ldsw + _i * 8192), 16, 0, 0); } while (0)
; #define PG8_LDA(dst, b, h) do { _Pragma("unroll") for (int m = 0; m < 4; ++m) _Pragma("unroll") for (int k = 0; k < 2; ++k) dst[m][k] = *(const LAS bf16x8*)(lds + PG8_SA(b, h) + aoff + m * 2048 + k * 1024); } while (0)
; #define PG8_LDB(dst, b, h) do { _Pragma("unroll") for (int n = 0; n < 2; ++n) _Pragma("unroll") for (int k = 0; k < 2; ++k) dst[n][k] = *(const LAS bf16x8*)(lds + PG8_SB(b, h) + boff + n * 2048 + k * 1024); } while (0)
; #define PG8_MMA(ai, bj, At, Bt) do { __builtin_amdgcn_s_setprio(1); _Pragma("unroll") for (int m = 0; m < 4; ++m) _Pragma("unroll") for (int n = 0; n < 2; ++n) _Pragma("unroll") for (int k = 0; k < 2; ++k) \
;         acc[ai][bj][m][n] = __builtin_amdgcn_mfma_f32_16x16x32_bf16(Bt[n][k], At[m][k], acc[ai][bj][m][n], 0, 0, 0); __builtin_amdgcn_s_setprio(0); } while (0)
; #define PG8_WAIT_V(n) asm volatile("s_waitcnt vmcnt(" #n ")" ::: "memory")
; #define PG8_WAIT_L(n) asm volatile("s_waitcnt lgkmcnt(" #n ")" ::: "memory")
; #define PG8_BAR __builtin_amdgcn_s_barrier()
; #define PG8_SCHED __builtin_amdgcn_sched_barrier(0)
; template <class Epi, class Sched>
; DI void gemm_phase(LAS unsigned char* lds, const Gemm g, const Sched& S, const Epi& E) {
;     ...
;             PG8_LDB(B0, 0, 0); PG8_LDB(B1, 0, 1); PG8_SCHED; PG8_LDA(At, 0, 0); PG8_STAGE(PG8_SA(1, 1), a1 + hstepA, voffA);
;             PG8_WAIT_V(8); PG8_WAIT_L(0); PG8_BAR; PG8_MMA(0, 0, At, B0); PG8_MMA(0, 1, At, B1); PG8_BAR; PG8_SCHED;
;             PG8_LDA(At, 0, 1); PG8_STAGE(PG8_SB(0, 0), b2, voffB); PG8_STAGE(PG8_SB(0, 1), b2 + hstepB, voffB); PG8_STAGE(PG8_SA(0, 0), a2, voffA);
;             PG8_WAIT_V(8); PG8_WAIT_L(0); PG8_BAR; PG8_MMA(1, 0, At, B0); PG8_MMA(1, 1, At, B1); PG8_BAR; PG8_SCHED;
;             PG8_LDB(B0, 1, 0); PG8_LDB(B1, 1, 1); PG8_SCHED; PG8_LDA(At, 1, 0); PG8_STAGE(PG8_SA(0, 1), a2 + hstepA, voffA);
;             PG8_WAIT_V(8); PG8_WAIT_L(0); PG8_BAR; PG8_MMA(0, 0, At, B0); PG8_MMA(0, 1, At, B1); PG8_BAR; PG8_SCHED;
.Lpk4_w2:
	s_mov_b32 s99, 0
	s_waitcnt lgkmcnt(0)
	s_barrier
	s_setprio 1
	v_mfma_f32_16x16x32_bf16 v[62:65], v[146:149], v[186:189], 0
	v_mfma_f32_16x16x32_bf16 v[58:61], v[160:163], v[186:189], 0
	v_mfma_f32_16x16x32_bf16 v[46:49], v[146:149], v[194:197], 0
	v_mfma_f32_16x16x32_bf16 v[42:45], v[160:163], v[194:197], 0
	v_mfma_f32_16x16x32_bf16 v[30:33], v[146:149], v[202:205], 0
	v_mfma_f32_16x16x32_bf16 v[26:29], v[160:163], v[202:205], 0
	v_mfma_f32_16x16x32_bf16 v[14:17], v[146:149], v[210:213], 0
	v_mfma_f32_16x16x32_bf16 v[10:13], v[160:163], v[210:213], 0
	v_mfma_f32_16x16x32_bf16 v[62:65], v[156:159], v[190:193], v[62:65]
	v_mfma_f32_16x16x32_bf16 v[58:61], v[164:167], v[190:193], v[58:61]
	v_mfma_f32_16x16x32_bf16 v[46:49], v[156:159], v[198:201], v[46:49]
	v_mfma_f32_16x16x32_bf16 v[42:45], v[164:167], v[198:201], v[42:45]
	v_mfma_f32_16x16x32_bf16 v[30:33], v[156:159], v[206:209], v[30:33]
	v_mfma_f32_16x16x32_bf16 v[26:29], v[164:167], v[206:209], v[26:29]
	v_mfma_f32_16x16x32_bf16 v[14:17], v[156:159], v[214:217], v[14:17]
	v_mfma_f32_16x16x32_bf16 v[10:13], v[164:167], v[214:217], v[10:13]
	v_mfma_f32_16x16x32_bf16 v[54:57], v[168:171], v[186:189], 0
	v_mfma_f32_16x16x32_bf16 v[50:53], v[176:179], v[186:189], 0
	v_mfma_f32_16x16x32_bf16 v[38:41], v[168:171], v[194:197], 0
	v_mfma_f32_16x16x32_bf16 v[34:37], v[176:179], v[194:197], 0
	v_mfma_f32_16x16x32_bf16 v[22:25], v[168:171], v[202:205], 0
	v_mfma_f32_16x16x32_bf16 v[18:21], v[176:179], v[202:205], 0
	v_mfma_f32_16x16x32_bf16 v[6:9], v[168:171], v[210:213], 0
	v_mfma_f32_16x16x32_bf16 v[2:5], v[176:179], v[210:213], 0
	v_mfma_f32_16x16x32_bf16 v[54:57], v[172:175], v[190:193], v[54:57]
	v_mfma_f32_16x16x32_bf16 v[50:53], v[180:183], v[190:193], v[50:53]
	v_mfma_f32_16x16x32_bf16 v[38:41], v[172:175], v[198:201], v[38:41]
	v_mfma_f32_16x16x32_bf16 v[34:37], v[180:183], v[198:201], v[34:37]
	v_mfma_f32_16x16x32_bf16 v[22:25], v[172:175], v[206:209], v[22:25]
	v_mfma_f32_16x16x32_bf16 v[18:21], v[180:183], v[206:209], v[18:21]
	v_mfma_f32_16x16x32_bf16 v[6:9], v[172:175], v[214:217], v[6:9]
	v_mfma_f32_16x16x32_bf16 v[2:5], v[180:183], v[214:217], v[2:5]
	s_setprio 0
	s_barrier
	s_add_i32 s67, 0, 0x18000
	s_add_i32 s68, 0, 0x1c000
	v_add_u32_e32 v164, s67, v150
	v_add_u32_e32 v180, s68, v150
	ds_read_b128 v[146:149], v164
	ds_read_b128 v[156:159], v164 offset:1024
	ds_read_b128 v[160:163], v164 offset:2048
	ds_read_b128 v[164:167], v164 offset:3072
	ds_read_b128 v[168:171], v180
	ds_read_b128 v[172:175], v180 offset:1024
	ds_read_b128 v[176:179], v180 offset:2048
	ds_read_b128 v[180:183], v180 offset:3072
	s_add_u32 s48, s48, 0x40000
	s_addc_u32 s49, s49, 0
	s_mov_b32 m0, s54
	v_lshl_add_u64 v[226:227], s[48:49], 0, v[130:131]
	ds_read_b128 v[186:189], v154 offset:32768
	ds_read_b128 v[190:193], v154 offset:33792
	ds_read_b128 v[194:197], v154 offset:34816
	ds_read_b128 v[198:201], v154 offset:35840
	ds_read_b128 v[202:205], v154 offset:36864
	ds_read_b128 v[206:209], v154 offset:37888
	ds_read_b128 v[210:213], v154 offset:38912
	ds_read_b128 v[214:217], v154 offset:39936
	global_load_lds_dwordx4 v[226:227], off
	v_lshl_add_u64 v[226:227], s[48:49], 0, v[134:135]
	s_mov_b32 m0, s55
	s_nop 0
	global_load_lds_dwordx4 v[226:227], off
	s_waitcnt vmcnt(8)
	s_waitcnt lgkmcnt(0)
	s_barrier
	s_setprio 1
	v_mfma_f32_16x16x32_bf16 v[126:129], v[146:149], v[186:189], v[126:129]
	v_mfma_f32_16x16x32_bf16 v[122:125], v[160:163], v[186:189], v[122:125]
	v_mfma_f32_16x16x32_bf16 v[110:113], v[146:149], v[194:197], v[110:113]
	v_mfma_f32_16x16x32_bf16 v[106:109], v[160:163], v[194:197], v[106:109]
	v_mfma_f32_16x16x32_bf16 v[94:97], v[146:149], v[202:205], v[94:97]
	v_mfma_f32_16x16x32_bf16 v[90:93], v[160:163], v[202:205], v[90:93]
	v_mfma_f32_16x16x32_bf16 v[78:81], v[146:149], v[210:213], v[78:81]
	v_mfma_f32_16x16x32_bf16 v[74:77], v[160:163], v[210:213], v[74:77]
	v_mfma_f32_16x16x32_bf16 v[126:129], v[156:159], v[190:193], v[126:129]
	v_mfma_f32_16x16x32_bf16 v[122:125], v[164:167], v[190:193], v[122:125]
	v_mfma_f32_16x16x32_bf16 v[110:113], v[156:159], v[198:201], v[110:113]
	v_mfma_f32_16x16x32_bf16 v[106:109], v[164:167], v[198:201], v[106:109]
	v_mfma_f32_16x16x32_bf16 v[94:97], v[156:159], v[206:209], v[94:97]
	v_mfma_f32_16x16x32_bf16 v[90:93], v[164:167], v[206:209], v[90:93]
	v_mfma_f32_16x16x32_bf16 v[78:81], v[156:159], v[214:217], v[78:81]
	v_mfma_f32_16x16x32_bf16 v[74:77], v[164:167], v[214:217], v[74:77]
	v_mfma_f32_16x16x32_bf16 v[118:121], v[168:171], v[186:189], v[118:121]
	v_mfma_f32_16x16x32_bf16 v[114:117], v[176:179], v[186:189], v[114:117]
	v_mfma_f32_16x16x32_bf16 v[102:105], v[168:171], v[194:197], v[102:105]
	v_mfma_f32_16x16x32_bf16 v[98:101], v[176:179], v[194:197], v[98:101]
	v_mfma_f32_16x16x32_bf16 v[86:89], v[168:171], v[202:205], v[86:89]
	v_mfma_f32_16x16x32_bf16 v[82:85], v[176:179], v[202:205], v[82:85]
	v_mfma_f32_16x16x32_bf16 v[70:73], v[168:171], v[210:213], v[70:73]
	v_mfma_f32_16x16x32_bf16 v[66:69], v[176:179], v[210:213], v[66:69]
	v_mfma_f32_16x16x32_bf16 v[118:121], v[172:175], v[190:193], v[118:121]
	v_mfma_f32_16x16x32_bf16 v[114:117], v[180:183], v[190:193], v[114:117]
	v_mfma_f32_16x16x32_bf16 v[102:105], v[172:175], v[198:201], v[102:105]
	v_mfma_f32_16x16x32_bf16 v[98:101], v[180:183], v[198:201], v[98:101]
	v_mfma_f32_16x16x32_bf16 v[86:89], v[172:175], v[206:209], v[86:89]
	v_mfma_f32_16x16x32_bf16 v[82:85], v[180:183], v[206:209], v[82:85]
	v_mfma_f32_16x16x32_bf16 v[70:73], v[172:175], v[214:217], v[70:73]
	v_mfma_f32_16x16x32_bf16 v[66:69], v[180:183], v[214:217], v[66:69]
	s_setprio 0
	s_barrier
; #define PG8_STAGE(bufoff, gbase, voff) do { _Pragma("unroll") for (int _i = 0; _i < 2; ++_i) \
;         __builtin_amdgcn_global_load_lds((const unsigned*)((const char*)(gbase) + (voff)[_i]), (LAS unsigned*)(lds + (bufoff) + ldsw + _i * 8192), 16, 0, 0); } while (0)
; #define PG8_LDA(dst, b, h) do { _Pragma("unroll") for (int m = 0; m < 4; ++m) _Pragma("unroll") for (int k = 0; k < 2; ++k) dst[m][k] = *(const LAS bf16x8*)(lds + PG8_SA(b, h) + aoff + m * 2048 + k * 1024); } while (0)
; #define PG8_MMA(ai, bj, At, Bt) do { __builtin_amdgcn_s_setprio(1); _Pragma("unroll") for (int m = 0; m < 4; ++m) _Pragma("unroll") for (int n = 0; n < 2; ++n) _Pragma("unroll") for (int k = 0; k < 2; ++k) \
;         acc[ai][bj][m][n] = __builtin_amdgcn_mfma_f32_16x16x32_bf16(Bt[n][k], At[m][k], acc[ai][bj][m][n], 0, 0, 0); __builtin_amdgcn_s_setprio(0); } while (0)
; #define PG8_WAIT_V(n) asm volatile("s_waitcnt vmcnt(" #n ")" ::: "memory")
; #define PG8_WAIT_L(n) asm volatile("s_waitcnt lgkmcnt(" #n ")" ::: "memory")
; #define PG8_BAR __builtin_amdgcn_s_barrier()
; #define PG8_SCHED __builtin_amdgcn_sched_barrier(0)
; template <class Epi, class Sched>
; DI void gemm_phase(LAS unsigned char* lds, const Gemm g, const Sched& S, const Epi& E) {
;     ...
;         for (int t = 0; t < nt; t += 2) {
;             const bool last = (t == nt - 2);
;             const char* a1 = cA + (size_t)(t + 1) * kstep;
;             const char* a2 = last ? nA : cA + (size_t)(t + 2) * kstep; const char* b2 = last ? nB : cB + (size_t)(t + 2) * kstep;
;             const char* a3 = a2 + kstep; const char* b3 = b2 + kstep;
;     ...
;             PG8_LDA(At, 1, 1); PG8_STAGE(PG8_SB(1, 0), b3, voffB); PG8_STAGE(PG8_SB(1, 1), b3 + hstepB, voffB); PG8_STAGE(PG8_SA(1, 0), a3, voffA);
;             PG8_WAIT_V(8); PG8_WAIT_L(0); PG8_BAR; PG8_MMA(1, 0, At, B0); PG8_MMA(1, 1, At, B1); PG8_BAR; PG8_SCHED;
	s_add_i32 s48, s67, s52
	v_lshl_add_u64 v[218:219], v[218:219], 0, s[16:17]
	s_mov_b32 m0, s48
	ds_read_b128 v[186:189], v154 offset:49152
	ds_read_b128 v[190:193], v154 offset:50176
	ds_read_b128 v[194:197], v154 offset:51200
	ds_read_b128 v[198:201], v154 offset:52224
	ds_read_b128 v[202:205], v154 offset:53248
	ds_read_b128 v[206:209], v154 offset:54272
	ds_read_b128 v[210:213], v154 offset:55296
	ds_read_b128 v[214:217], v154 offset:56320
	global_load_lds_dwordx4 v[218:219], off
	s_add_i32 m0, s48, 0x2000
	s_add_u32 s46, s46, 0x40080
	v_lshl_add_u64 v[218:219], v[220:221], 0, s[16:17]
	s_addc_u32 s47, s47, 0
	s_add_i32 s48, s68, s52
	global_load_lds_dwordx4 v[218:219], off
	v_lshl_add_u64 v[218:219], s[46:47], 0, v[132:133]
	s_mov_b32 m0, s48
	s_nop 0
	global_load_lds_dwordx4 v[218:219], off
	v_lshl_add_u64 v[218:219], s[46:47], 0, v[136:137]
	s_add_i32 m0, s48, 0x2000
	s_nop 0
	global_load_lds_dwordx4 v[218:219], off
	v_lshl_add_u64 v[218:219], v[222:223], 0, s[16:17]
	s_mov_b32 m0, s57
	s_nop 0
	global_load_lds_dwordx4 v[218:219], off
	v_lshl_add_u64 v[218:219], v[224:225], 0, s[16:17]
	s_mov_b32 m0, s58
	s_nop 0
	global_load_lds_dwordx4 v[218:219], off
	s_waitcnt vmcnt(8)
	s_waitcnt lgkmcnt(0)
	s_barrier
	s_setprio 1
	v_mfma_f32_16x16x32_bf16 v[62:65], v[146:149], v[186:189], v[62:65]
	v_mfma_f32_16x16x32_bf16 v[58:61], v[160:163], v[186:189], v[58:61]
	v_mfma_f32_16x16x32_bf16 v[46:49], v[146:149], v[194:197], v[46:49]
	v_mfma_f32_16x16x32_bf16 v[42:45], v[160:163], v[194:197], v[42:45]
	v_mfma_f32_16x16x32_bf16 v[30:33], v[146:149], v[202:205], v[30:33]
	v_mfma_f32_16x16x32_bf16 v[26:29], v[160:163], v[202:205], v[26:29]
	v_mfma_f32_16x16x32_bf16 v[14:17], v[146:149], v[210:213], v[14:17]
	v_mfma_f32_16x16x32_bf16 v[10:13], v[160:163], v[210:213], v[10:13]
	v_mfma_f32_16x16x32_bf16 v[62:65], v[156:159], v[190:193], v[62:65]
	v_mfma_f32_16x16x32_bf16 v[58:61], v[164:167], v[190:193], v[58:61]
	v_mfma_f32_16x16x32_bf16 v[46:49], v[156:159], v[198:201], v[46:49]
	v_mfma_f32_16x16x32_bf16 v[42:45], v[164:167], v[198:201], v[42:45]
	v_mfma_f32_16x16x32_bf16 v[30:33], v[156:159], v[206:209], v[30:33]
	v_mfma_f32_16x16x32_bf16 v[26:29], v[164:167], v[206:209], v[26:29]
	v_mfma_f32_16x16x32_bf16 v[14:17], v[156:159], v[214:217], v[14:17]
	v_mfma_f32_16x16x32_bf16 v[10:13], v[164:167], v[214:217], v[10:13]
	v_mfma_f32_16x16x32_bf16 v[54:57], v[168:171], v[186:189], v[54:57]
	v_mfma_f32_16x16x32_bf16 v[50:53], v[176:179], v[186:189], v[50:53]
	v_mfma_f32_16x16x32_bf16 v[38:41], v[168:171], v[194:197], v[38:41]
	v_mfma_f32_16x16x32_bf16 v[34:37], v[176:179], v[194:197], v[34:37]
	v_mfma_f32_16x16x32_bf16 v[22:25], v[168:171], v[202:205], v[22:25]
	v_mfma_f32_16x16x32_bf16 v[18:21], v[176:179], v[202:205], v[18:21]
	v_mfma_f32_16x16x32_bf16 v[6:9], v[168:171], v[210:213], v[6:9]
	v_mfma_f32_16x16x32_bf16 v[2:5], v[176:179], v[210:213], v[2:5]
	v_mfma_f32_16x16x32_bf16 v[54:57], v[172:175], v[190:193], v[54:57]
	v_mfma_f32_16x16x32_bf16 v[50:53], v[180:183], v[190:193], v[50:53]
	v_mfma_f32_16x16x32_bf16 v[38:41], v[172:175], v[198:201], v[38:41]
	v_mfma_f32_16x16x32_bf16 v[34:37], v[180:183], v[198:201], v[34:37]
	v_mfma_f32_16x16x32_bf16 v[22:25], v[172:175], v[206:209], v[22:25]
	v_mfma_f32_16x16x32_bf16 v[18:21], v[180:183], v[206:209], v[18:21]
	v_mfma_f32_16x16x32_bf16 v[6:9], v[172:175], v[214:217], v[6:9]
	v_mfma_f32_16x16x32_bf16 v[2:5], v[180:183], v[214:217], v[2:5]
	s_setprio 0
	s_barrier
	s_add_i32 s66, s66, 2
	s_add_u32 s44, s44, 0x100
	s_addc_u32 s45, s45, 0
	s_add_u32 s64, s64, 0x100
	s_addc_u32 s65, s65, 0
	s_cmp_gt_u32 s66, 13
	.p2alignl 6, 3212836864

; #define PG8_STAGE(bufoff, gbase, voff) do { _Pragma("unroll") for (int _i = 0; _i < 2; ++_i) \
;         __builtin_amdgcn_global_load_lds((const unsigned*)((const char*)(gbase) + (voff)[_i]), (LAS unsigned*)(lds + (bufoff) + ldsw + _i * 8192), 16, 0, 0); } while (0)
; #define PG8_LDA(dst, b, h) do { _Pragma("unroll") for (int m = 0; m < 4; ++m) _Pragma("unroll") for (int k = 0; k < 2; ++k) dst[m][k] = *(const LAS bf16x8*)(lds + PG8_SA(b, h) + aoff + m * 2048 + k * 1024); } while (0)
; #define PG8_LDB(dst, b, h) do { _Pragma("unroll") for (int n = 0; n < 2; ++n) _Pragma("unroll") for (int k = 0; k < 2; ++k) dst[n][k] = *(const LAS bf16x8*)(lds + PG8_SB(b, h) + boff + n * 2048 + k * 1024); } while (0)
; #define PG8_MMA(ai, bj, At, Bt) do { __builtin_amdgcn_s_setprio(1); _Pragma("unroll") for (int m = 0; m < 4; ++m) _Pragma("unroll") for (int n = 0; n < 2; ++n) _Pragma("unroll") for (int k = 0; k < 2; ++k) \
;         acc[ai][bj][m][n] = __builtin_amdgcn_mfma_f32_16x16x32_bf16(Bt[n][k], At[m][k], acc[ai][bj][m][n], 0, 0, 0); __builtin_amdgcn_s_setprio(0); } while (0)
; #define PG8_WAIT_V(n) asm volatile("s_waitcnt vmcnt(" #n ")" ::: "memory")
; #define PG8_WAIT_L(n) asm volatile("s_waitcnt lgkmcnt(" #n ")" ::: "memory")
; #define PG8_BAR __builtin_amdgcn_s_barrier()
; #define PG8_SCHED __builtin_amdgcn_sched_barrier(0)
; template <class Epi, class Sched>
; DI void gemm_phase(LAS unsigned char* lds, const Gemm g, const Sched& S, const Epi& E) {
;     ...
;             PG8_LDB(B0, 0, 0); PG8_LDB(B1, 0, 1); PG8_SCHED; PG8_LDA(At, 0, 0); PG8_STAGE(PG8_SA(1, 1), a1 + hstepA, voffA);
;             PG8_WAIT_V(8); PG8_WAIT_L(0); PG8_BAR; PG8_MMA(0, 0, At, B0); PG8_MMA(0, 1, At, B1); PG8_BAR; PG8_SCHED;
;             PG8_LDA(At, 0, 1); PG8_STAGE(PG8_SB(0, 0), b2, voffB); PG8_STAGE(PG8_SB(0, 1), b2 + hstepB, voffB); PG8_STAGE(PG8_SA(0, 0), a2, voffA);
;             PG8_WAIT_V(8); PG8_WAIT_L(0); PG8_BAR; PG8_MMA(1, 0, At, B0); PG8_MMA(1, 1, At, B1); PG8_BAR; PG8_SCHED;
;             PG8_LDB(B0, 1, 0); PG8_LDB(B1, 1, 1); PG8_SCHED; PG8_LDA(At, 1, 0); PG8_STAGE(PG8_SA(0, 1), a2 + hstepA, voffA);
;             PG8_WAIT_V(8); PG8_WAIT_L(0); PG8_BAR; PG8_MMA(0, 0, At, B0); PG8_MMA(0, 1, At, B1); PG8_BAR; PG8_SCHED;
.Lpk5_w2:
	s_mov_b32 s99, 0
	s_waitcnt lgkmcnt(0)
	s_barrier
	s_setprio 1
	v_mfma_f32_16x16x32_bf16 v[62:65], v[166:169], v[202:205], 0
	v_mfma_f32_16x16x32_bf16 v[54:57], v[174:177], v[202:205], 0
	v_mfma_f32_16x16x32_bf16 v[46:49], v[166:169], v[210:213], 0
	v_mfma_f32_16x16x32_bf16 v[38:41], v[174:177], v[210:213], 0
	v_mfma_f32_16x16x32_bf16 v[30:33], v[166:169], v[218:221], 0
	v_mfma_f32_16x16x32_bf16 v[22:25], v[174:177], v[218:221], 0
	v_mfma_f32_16x16x32_bf16 v[14:17], v[166:169], v[226:229], 0
	v_mfma_f32_16x16x32_bf16 v[6:9], v[174:177], v[226:229], 0
	v_mfma_f32_16x16x32_bf16 v[62:65], v[170:173], v[206:209], v[62:65]
	v_mfma_f32_16x16x32_bf16 v[54:57], v[178:181], v[206:209], v[54:57]
	v_mfma_f32_16x16x32_bf16 v[46:49], v[170:173], v[214:217], v[46:49]
	v_mfma_f32_16x16x32_bf16 v[38:41], v[178:181], v[214:217], v[38:41]
	v_mfma_f32_16x16x32_bf16 v[30:33], v[170:173], v[222:225], v[30:33]
	v_mfma_f32_16x16x32_bf16 v[22:25], v[178:181], v[222:225], v[22:25]
	v_mfma_f32_16x16x32_bf16 v[14:17], v[170:173], v[230:233], v[14:17]
	v_mfma_f32_16x16x32_bf16 v[6:9], v[178:181], v[230:233], v[6:9]
	v_mfma_f32_16x16x32_bf16 v[58:61], v[186:189], v[202:205], 0
	v_mfma_f32_16x16x32_bf16 v[50:53], v[194:197], v[202:205], 0
	v_mfma_f32_16x16x32_bf16 v[42:45], v[186:189], v[210:213], 0
	v_mfma_f32_16x16x32_bf16 v[34:37], v[194:197], v[210:213], 0
	v_mfma_f32_16x16x32_bf16 v[26:29], v[186:189], v[218:221], 0
	v_mfma_f32_16x16x32_bf16 v[18:21], v[194:197], v[218:221], 0
	v_mfma_f32_16x16x32_bf16 v[10:13], v[186:189], v[226:229], 0
	v_mfma_f32_16x16x32_bf16 v[2:5], v[194:197], v[226:229], 0
	v_mfma_f32_16x16x32_bf16 v[58:61], v[190:193], v[206:209], v[58:61]
	v_mfma_f32_16x16x32_bf16 v[50:53], v[198:201], v[206:209], v[50:53]
	v_mfma_f32_16x16x32_bf16 v[42:45], v[190:193], v[214:217], v[42:45]
	v_mfma_f32_16x16x32_bf16 v[34:37], v[198:201], v[214:217], v[34:37]
	v_mfma_f32_16x16x32_bf16 v[26:29], v[190:193], v[222:225], v[26:29]
	v_mfma_f32_16x16x32_bf16 v[18:21], v[198:201], v[222:225], v[18:21]
	v_mfma_f32_16x16x32_bf16 v[10:13], v[190:193], v[230:233], v[10:13]
	v_mfma_f32_16x16x32_bf16 v[2:5], v[198:201], v[230:233], v[2:5]
	s_setprio 0
	s_barrier
	s_add_i32 s66, 0, 0x18000
	v_add_u32_e32 v165, s66, v156
	s_add_i32 s67, 0, 0x1c000
	ds_read_b128 v[166:169], v165
	ds_read_b128 v[170:173], v165 offset:1024
	ds_read_b128 v[174:177], v165 offset:2048
	ds_read_b128 v[178:181], v165 offset:3072
	v_add_u32_e32 v165, s67, v156
	ds_read_b128 v[186:189], v165
	ds_read_b128 v[190:193], v165 offset:1024
	ds_read_b128 v[194:197], v165 offset:2048
	ds_read_b128 v[198:201], v165 offset:3072
	s_add_u32 s44, s44, 0x40000
	s_addc_u32 s45, s45, 0
	s_mov_b32 m0, s51
	v_lshl_add_u64 v[240:241], s[44:45], 0, v[136:137]
	ds_read_b128 v[202:205], v158 offset:32768
	ds_read_b128 v[206:209], v158 offset:33792
	ds_read_b128 v[210:213], v158 offset:34816
	ds_read_b128 v[214:217], v158 offset:35840
	ds_read_b128 v[218:221], v158 offset:36864
	ds_read_b128 v[222:225], v158 offset:37888
	ds_read_b128 v[226:229], v158 offset:38912
	ds_read_b128 v[230:233], v158 offset:39936
	global_load_lds_dwordx4 v[240:241], off
	v_lshl_add_u64 v[240:241], s[44:45], 0, v[132:133]
	s_mov_b32 m0, s52
	s_nop 0
	global_load_lds_dwordx4 v[240:241], off
	s_waitcnt vmcnt(8)
	s_waitcnt lgkmcnt(0)
	s_barrier
	s_setprio 1
	v_mfma_f32_16x16x32_bf16 v[126:129], v[166:169], v[202:205], v[126:129]
	v_mfma_f32_16x16x32_bf16 v[118:121], v[174:177], v[202:205], v[118:121]
	v_mfma_f32_16x16x32_bf16 v[110:113], v[166:169], v[210:213], v[110:113]
	v_mfma_f32_16x16x32_bf16 v[102:105], v[174:177], v[210:213], v[102:105]
	v_mfma_f32_16x16x32_bf16 v[94:97], v[166:169], v[218:221], v[94:97]
	v_mfma_f32_16x16x32_bf16 v[86:89], v[174:177], v[218:221], v[86:89]
	v_mfma_f32_16x16x32_bf16 v[78:81], v[166:169], v[226:229], v[78:81]
	v_mfma_f32_16x16x32_bf16 v[70:73], v[174:177], v[226:229], v[70:73]
	v_mfma_f32_16x16x32_bf16 v[126:129], v[170:173], v[206:209], v[126:129]
	v_mfma_f32_16x16x32_bf16 v[118:121], v[178:181], v[206:209], v[118:121]
	v_mfma_f32_16x16x32_bf16 v[110:113], v[170:173], v[214:217], v[110:113]
	v_mfma_f32_16x16x32_bf16 v[102:105], v[178:181], v[214:217], v[102:105]
	v_mfma_f32_16x16x32_bf16 v[94:97], v[170:173], v[222:225], v[94:97]
	v_mfma_f32_16x16x32_bf16 v[86:89], v[178:181], v[222:225], v[86:89]
	v_mfma_f32_16x16x32_bf16 v[78:81], v[170:173], v[230:233], v[78:81]
	v_mfma_f32_16x16x32_bf16 v[70:73], v[178:181], v[230:233], v[70:73]
	v_mfma_f32_16x16x32_bf16 v[122:125], v[186:189], v[202:205], v[122:125]
	v_mfma_f32_16x16x32_bf16 v[114:117], v[194:197], v[202:205], v[114:117]
	v_mfma_f32_16x16x32_bf16 v[106:109], v[186:189], v[210:213], v[106:109]
	v_mfma_f32_16x16x32_bf16 v[98:101], v[194:197], v[210:213], v[98:101]
	v_mfma_f32_16x16x32_bf16 v[90:93], v[186:189], v[218:221], v[90:93]
	v_mfma_f32_16x16x32_bf16 v[82:85], v[194:197], v[218:221], v[82:85]
	v_mfma_f32_16x16x32_bf16 v[74:77], v[186:189], v[226:229], v[74:77]
	v_mfma_f32_16x16x32_bf16 v[66:69], v[194:197], v[226:229], v[66:69]
	v_mfma_f32_16x16x32_bf16 v[122:125], v[190:193], v[206:209], v[122:125]
	v_mfma_f32_16x16x32_bf16 v[114:117], v[198:201], v[206:209], v[114:117]
	v_mfma_f32_16x16x32_bf16 v[106:109], v[190:193], v[214:217], v[106:109]
	v_mfma_f32_16x16x32_bf16 v[98:101], v[198:201], v[214:217], v[98:101]
	v_mfma_f32_16x16x32_bf16 v[90:93], v[190:193], v[222:225], v[90:93]
	v_mfma_f32_16x16x32_bf16 v[82:85], v[198:201], v[222:225], v[82:85]
	v_mfma_f32_16x16x32_bf16 v[74:77], v[190:193], v[230:233], v[74:77]
	v_mfma_f32_16x16x32_bf16 v[66:69], v[198:201], v[230:233], v[66:69]
	s_setprio 0
	s_barrier
; #define PG8_STAGE(bufoff, gbase, voff) do { _Pragma("unroll") for (int _i = 0; _i < 2; ++_i) \
;         __builtin_amdgcn_global_load_lds((const unsigned*)((const char*)(gbase) + (voff)[_i]), (LAS unsigned*)(lds + (bufoff) + ldsw + _i * 8192), 16, 0, 0); } while (0)
; #define PG8_LDA(dst, b, h) do { _Pragma("unroll") for (int m = 0; m < 4; ++m) _Pragma("unroll") for (int k = 0; k < 2; ++k) dst[m][k] = *(const LAS bf16x8*)(lds + PG8_SA(b, h) + aoff + m * 2048 + k * 1024); } while (0)
; #define PG8_MMA(ai, bj, At, Bt) do { __builtin_amdgcn_s_setprio(1); _Pragma("unroll") for (int m = 0; m < 4; ++m) _Pragma("unroll") for (int n = 0; n < 2; ++n) _Pragma("unroll") for (int k = 0; k < 2; ++k) \
;         acc[ai][bj][m][n] = __builtin_amdgcn_mfma_f32_16x16x32_bf16(Bt[n][k], At[m][k], acc[ai][bj][m][n], 0, 0, 0); __builtin_amdgcn_s_setprio(0); } while (0)
; #define PG8_WAIT_V(n) asm volatile("s_waitcnt vmcnt(" #n ")" ::: "memory")
; #define PG8_WAIT_L(n) asm volatile("s_waitcnt lgkmcnt(" #n ")" ::: "memory")
; #define PG8_BAR __builtin_amdgcn_s_barrier()
; #define PG8_SCHED __builtin_amdgcn_sched_barrier(0)
; template <class Epi, class Sched>
; DI void gemm_phase(LAS unsigned char* lds, const Gemm g, const Sched& S, const Epi& E) {
;     ...
;         for (int t = 0; t < nt; t += 2) {
;             const bool last = (t == nt - 2);
;             const char* a1 = cA + (size_t)(t + 1) * kstep;
;             const char* a2 = last ? nA : cA + (size_t)(t + 2) * kstep; const char* b2 = last ? nB : cB + (size_t)(t + 2) * kstep;
;             const char* a3 = a2 + kstep; const char* b3 = b2 + kstep;
;     ...
;             PG8_LDA(At, 1, 1); PG8_STAGE(PG8_SB(1, 0), b3, voffB); PG8_STAGE(PG8_SB(1, 1), b3 + hstepB, voffB); PG8_STAGE(PG8_SA(1, 0), a3, voffA);
;             PG8_WAIT_V(8); PG8_WAIT_L(0); PG8_BAR; PG8_MMA(1, 0, At, B0); PG8_MMA(1, 1, At, B1); PG8_BAR; PG8_SCHED;
	s_add_i32 s44, s66, s46
	v_lshl_add_u64 v[182:183], v[182:183], 0, s[16:17]
	s_mov_b32 m0, s44
	ds_read_b128 v[202:205], v158 offset:49152
	ds_read_b128 v[206:209], v158 offset:50176
	ds_read_b128 v[210:213], v158 offset:51200
	ds_read_b128 v[214:217], v158 offset:52224
	ds_read_b128 v[218:221], v158 offset:53248
	ds_read_b128 v[222:225], v158 offset:54272
	ds_read_b128 v[226:229], v158 offset:55296
	ds_read_b128 v[230:233], v158 offset:56320
	global_load_lds_dwordx4 v[182:183], off
	s_add_i32 m0, s44, 0x2000
	s_add_u32 s42, s42, 0x40080
	v_lshl_add_u64 v[182:183], v[234:235], 0, s[16:17]
	s_addc_u32 s43, s43, 0
	s_add_i32 s44, s67, s46
	global_load_lds_dwordx4 v[182:183], off
	v_lshl_add_u64 v[182:183], s[42:43], 0, v[134:135]
	s_mov_b32 m0, s44
	s_nop 0
	global_load_lds_dwordx4 v[182:183], off
	v_lshl_add_u64 v[182:183], s[42:43], 0, v[130:131]
	s_add_i32 m0, s44, 0x2000
	s_nop 0
	global_load_lds_dwordx4 v[182:183], off
	v_lshl_add_u64 v[182:183], v[236:237], 0, s[16:17]
	s_mov_b32 m0, s54
	s_nop 0
	global_load_lds_dwordx4 v[182:183], off
	v_lshl_add_u64 v[182:183], v[238:239], 0, s[16:17]
	s_mov_b32 m0, s55
	s_nop 0
	global_load_lds_dwordx4 v[182:183], off
	s_waitcnt vmcnt(8)
	s_waitcnt lgkmcnt(0)
	s_barrier
	s_setprio 1
	v_mfma_f32_16x16x32_bf16 v[62:65], v[166:169], v[202:205], v[62:65]
	v_mfma_f32_16x16x32_bf16 v[54:57], v[174:177], v[202:205], v[54:57]
	v_mfma_f32_16x16x32_bf16 v[46:49], v[166:169], v[210:213], v[46:49]
	v_mfma_f32_16x16x32_bf16 v[38:41], v[174:177], v[210:213], v[38:41]
	v_mfma_f32_16x16x32_bf16 v[30:33], v[166:169], v[218:221], v[30:33]
	v_mfma_f32_16x16x32_bf16 v[22:25], v[174:177], v[218:221], v[22:25]
	v_mfma_f32_16x16x32_bf16 v[14:17], v[166:169], v[226:229], v[14:17]
	v_mfma_f32_16x16x32_bf16 v[6:9], v[174:177], v[226:229], v[6:9]
	v_mfma_f32_16x16x32_bf16 v[62:65], v[170:173], v[206:209], v[62:65]
	v_mfma_f32_16x16x32_bf16 v[54:57], v[178:181], v[206:209], v[54:57]
	v_mfma_f32_16x16x32_bf16 v[46:49], v[170:173], v[214:217], v[46:49]
	v_mfma_f32_16x16x32_bf16 v[38:41], v[178:181], v[214:217], v[38:41]
	v_mfma_f32_16x16x32_bf16 v[30:33], v[170:173], v[222:225], v[30:33]
	v_mfma_f32_16x16x32_bf16 v[22:25], v[178:181], v[222:225], v[22:25]
	v_mfma_f32_16x16x32_bf16 v[14:17], v[170:173], v[230:233], v[14:17]
	v_mfma_f32_16x16x32_bf16 v[6:9], v[178:181], v[230:233], v[6:9]
	v_mfma_f32_16x16x32_bf16 v[58:61], v[186:189], v[202:205], v[58:61]
	v_mfma_f32_16x16x32_bf16 v[50:53], v[194:197], v[202:205], v[50:53]
	v_mfma_f32_16x16x32_bf16 v[42:45], v[186:189], v[210:213], v[42:45]
	v_mfma_f32_16x16x32_bf16 v[34:37], v[194:197], v[210:213], v[34:37]
	v_mfma_f32_16x16x32_bf16 v[26:29], v[186:189], v[218:221], v[26:29]
	v_mfma_f32_16x16x32_bf16 v[18:21], v[194:197], v[218:221], v[18:21]
	v_mfma_f32_16x16x32_bf16 v[10:13], v[186:189], v[226:229], v[10:13]
	v_mfma_f32_16x16x32_bf16 v[2:5], v[194:197], v[226:229], v[2:5]
	v_mfma_f32_16x16x32_bf16 v[58:61], v[190:193], v[206:209], v[58:61]
	v_mfma_f32_16x16x32_bf16 v[50:53], v[198:201], v[206:209], v[50:53]
	v_mfma_f32_16x16x32_bf16 v[42:45], v[190:193], v[214:217], v[42:45]
	v_mfma_f32_16x16x32_bf16 v[34:37], v[198:201], v[214:217], v[34:37]
	v_mfma_f32_16x16x32_bf16 v[26:29], v[190:193], v[222:225], v[26:29]
	v_mfma_f32_16x16x32_bf16 v[18:21], v[198:201], v[222:225], v[18:21]
	v_mfma_f32_16x16x32_bf16 v[10:13], v[190:193], v[230:233], v[10:13]
	v_mfma_f32_16x16x32_bf16 v[2:5], v[198:201], v[230:233], v[2:5]
	s_setprio 0
	s_barrier
	s_add_i32 s65, s65, 2
	s_add_u32 s40, s40, 0x100
	s_addc_u32 s41, s41, 0
	s_add_u32 s63, s63, 0x100
	s_addc_u32 s64, s64, 0
	s_cmp_gt_u32 s65, 13
	.p2alignl 6, 3212836864

; #define PG8_STAGE(bufoff, gbase, voff) do { _Pragma("unroll") for (int _i = 0; _i < 2; ++_i) \
;         __builtin_amdgcn_global_load_lds((const unsigned*)((const char*)(gbase) + (voff)[_i]), (LAS unsigned*)(lds + (bufoff) + ldsw + _i * 8192), 16, 0, 0); } while (0)
; #define PG8_LDA(dst, b, h) do { _Pragma("unroll") for (int m = 0; m < 4; ++m) _Pragma("unroll") for (int k = 0; k < 2; ++k) dst[m][k] = *(const LAS bf16x8*)(lds + PG8_SA(b, h) + aoff + m * 2048 + k * 1024); } while (0)
; #define PG8_LDB(dst, b, h) do { _Pragma("unroll") for (int n = 0; n < 2; ++n) _Pragma("unroll") for (int k = 0; k < 2; ++k) dst[n][k] = *(const LAS bf16x8*)(lds + PG8_SB(b, h) + boff + n * 2048 + k * 1024); } while (0)
; #define PG8_MMA(ai, bj, At, Bt) do { __builtin_amdgcn_s_setprio(1); _Pragma("unroll") for (int m = 0; m < 4; ++m) _Pragma("unroll") for (int n = 0; n < 2; ++n) _Pragma("unroll") for (int k = 0; k < 2; ++k) \
;         acc[ai][bj][m][n] = __builtin_amdgcn_mfma_f32_16x16x32_bf16(Bt[n][k], At[m][k], acc[ai][bj][m][n], 0, 0, 0); __builtin_amdgcn_s_setprio(0); } while (0)
; #define PG8_WAIT_V(n) asm volatile("s_waitcnt vmcnt(" #n ")" ::: "memory")
; #define PG8_WAIT_L(n) asm volatile("s_waitcnt lgkmcnt(" #n ")" ::: "memory")
; #define PG8_BAR __builtin_amdgcn_s_barrier()
; #define PG8_SCHED __builtin_amdgcn_sched_barrier(0)
; template <class Epi, class Sched>
; DI void gemm_phase(LAS unsigned char* lds, const Gemm g, const Sched& S, const Epi& E) {
;     ...
;             PG8_LDB(B0, 0, 0); PG8_LDB(B1, 0, 1); PG8_SCHED; PG8_LDA(At, 0, 0); PG8_STAGE(PG8_SA(1, 1), a1 + hstepA, voffA);
;             PG8_WAIT_V(8); PG8_WAIT_L(0); PG8_BAR; PG8_MMA(0, 0, At, B0); PG8_MMA(0, 1, At, B1); PG8_BAR; PG8_SCHED;
;             PG8_LDA(At, 0, 1); PG8_STAGE(PG8_SB(0, 0), b2, voffB); PG8_STAGE(PG8_SB(0, 1), b2 + hstepB, voffB); PG8_STAGE(PG8_SA(0, 0), a2, voffA);
;             PG8_WAIT_V(8); PG8_WAIT_L(0); PG8_BAR; PG8_MMA(1, 0, At, B0); PG8_MMA(1, 1, At, B1); PG8_BAR; PG8_SCHED;
;             PG8_LDB(B0, 1, 0); PG8_LDB(B1, 1, 1); PG8_SCHED; PG8_LDA(At, 1, 0); PG8_STAGE(PG8_SA(0, 1), a2 + hstepA, voffA);
;             PG8_WAIT_V(8); PG8_WAIT_L(0); PG8_BAR; PG8_MMA(0, 0, At, B0); PG8_MMA(0, 1, At, B1); PG8_BAR; PG8_SCHED;
.Lpk6_w2:
	s_mov_b32 s99, 0
	s_waitcnt lgkmcnt(0)
	s_barrier
	s_setprio 1
	v_mfma_f32_16x16x32_bf16 v[60:63], v[144:147], v[182:185], 0
	v_mfma_f32_16x16x32_bf16 v[56:59], v[158:161], v[182:185], 0
	v_mfma_f32_16x16x32_bf16 v[44:47], v[144:147], v[190:193], 0
	v_mfma_f32_16x16x32_bf16 v[40:43], v[158:161], v[190:193], 0
	v_mfma_f32_16x16x32_bf16 v[28:31], v[144:147], v[198:201], 0
	v_mfma_f32_16x16x32_bf16 v[24:27], v[158:161], v[198:201], 0
	v_mfma_f32_16x16x32_bf16 v[12:15], v[144:147], v[206:209], 0
	v_mfma_f32_16x16x32_bf16 v[8:11], v[158:161], v[206:209], 0
	v_mfma_f32_16x16x32_bf16 v[60:63], v[154:157], v[186:189], v[60:63]
	v_mfma_f32_16x16x32_bf16 v[56:59], v[162:165], v[186:189], v[56:59]
	v_mfma_f32_16x16x32_bf16 v[44:47], v[154:157], v[194:197], v[44:47]
	v_mfma_f32_16x16x32_bf16 v[40:43], v[162:165], v[194:197], v[40:43]
	v_mfma_f32_16x16x32_bf16 v[28:31], v[154:157], v[202:205], v[28:31]
	v_mfma_f32_16x16x32_bf16 v[24:27], v[162:165], v[202:205], v[24:27]
	v_mfma_f32_16x16x32_bf16 v[12:15], v[154:157], v[210:213], v[12:15]
	v_mfma_f32_16x16x32_bf16 v[8:11], v[162:165], v[210:213], v[8:11]
	v_mfma_f32_16x16x32_bf16 v[52:55], v[166:169], v[182:185], 0
	v_mfma_f32_16x16x32_bf16 v[48:51], v[174:177], v[182:185], 0
	v_mfma_f32_16x16x32_bf16 v[36:39], v[166:169], v[190:193], 0
	v_mfma_f32_16x16x32_bf16 v[32:35], v[174:177], v[190:193], 0
	v_mfma_f32_16x16x32_bf16 v[20:23], v[166:169], v[198:201], 0
	v_mfma_f32_16x16x32_bf16 v[16:19], v[174:177], v[198:201], 0
	v_mfma_f32_16x16x32_bf16 v[4:7], v[166:169], v[206:209], 0
	v_mfma_f32_16x16x32_bf16 v[0:3], v[174:177], v[206:209], 0
	v_mfma_f32_16x16x32_bf16 v[52:55], v[170:173], v[186:189], v[52:55]
	v_mfma_f32_16x16x32_bf16 v[48:51], v[178:181], v[186:189], v[48:51]
	v_mfma_f32_16x16x32_bf16 v[36:39], v[170:173], v[194:197], v[36:39]
	v_mfma_f32_16x16x32_bf16 v[32:35], v[178:181], v[194:197], v[32:35]
	v_mfma_f32_16x16x32_bf16 v[20:23], v[170:173], v[202:205], v[20:23]
	v_mfma_f32_16x16x32_bf16 v[16:19], v[178:181], v[202:205], v[16:19]
	v_mfma_f32_16x16x32_bf16 v[4:7], v[170:173], v[210:213], v[4:7]
	v_mfma_f32_16x16x32_bf16 v[0:3], v[178:181], v[210:213], v[0:3]
	s_setprio 0
	s_barrier
	s_add_i32 s48, 0, 0x18000
	s_add_i32 s49, 0, 0x1c000
	v_add_u32_e32 v162, s48, v149
	v_add_u32_e32 v178, s49, v149
	ds_read_b128 v[144:147], v162
	ds_read_b128 v[154:157], v162 offset:1024
	ds_read_b128 v[158:161], v162 offset:2048
	ds_read_b128 v[162:165], v162 offset:3072
	ds_read_b128 v[166:169], v178
	ds_read_b128 v[170:173], v178 offset:1024
	ds_read_b128 v[174:177], v178 offset:2048
	ds_read_b128 v[178:181], v178 offset:3072
	s_add_u32 s20, s20, 0xb0000
	s_addc_u32 s21, s21, 0
	s_mov_b32 m0, s33
	v_lshl_add_u64 v[222:223], s[20:21], 0, v[128:129]
	ds_read_b128 v[182:185], v153 offset:32768
	ds_read_b128 v[186:189], v153 offset:33792
	ds_read_b128 v[190:193], v153 offset:34816
	ds_read_b128 v[194:197], v153 offset:35840
	ds_read_b128 v[198:201], v153 offset:36864
	ds_read_b128 v[202:205], v153 offset:37888
	ds_read_b128 v[206:209], v153 offset:38912
	ds_read_b128 v[210:213], v153 offset:39936
	global_load_lds_dwordx4 v[222:223], off
	v_lshl_add_u64 v[222:223], s[20:21], 0, v[132:133]
	s_mov_b32 m0, s34
	s_nop 0
	global_load_lds_dwordx4 v[222:223], off
	s_waitcnt vmcnt(8)
	s_waitcnt lgkmcnt(0)
	s_barrier
	s_setprio 1
	v_mfma_f32_16x16x32_bf16 v[124:127], v[144:147], v[182:185], v[124:127]
	v_mfma_f32_16x16x32_bf16 v[120:123], v[158:161], v[182:185], v[120:123]
	v_mfma_f32_16x16x32_bf16 v[108:111], v[144:147], v[190:193], v[108:111]
	v_mfma_f32_16x16x32_bf16 v[104:107], v[158:161], v[190:193], v[104:107]
	v_mfma_f32_16x16x32_bf16 v[92:95], v[144:147], v[198:201], v[92:95]
	v_mfma_f32_16x16x32_bf16 v[88:91], v[158:161], v[198:201], v[88:91]
	v_mfma_f32_16x16x32_bf16 v[76:79], v[144:147], v[206:209], v[76:79]
	v_mfma_f32_16x16x32_bf16 v[72:75], v[158:161], v[206:209], v[72:75]
	v_mfma_f32_16x16x32_bf16 v[124:127], v[154:157], v[186:189], v[124:127]
	v_mfma_f32_16x16x32_bf16 v[120:123], v[162:165], v[186:189], v[120:123]
	v_mfma_f32_16x16x32_bf16 v[108:111], v[154:157], v[194:197], v[108:111]
	v_mfma_f32_16x16x32_bf16 v[104:107], v[162:165], v[194:197], v[104:107]
	v_mfma_f32_16x16x32_bf16 v[92:95], v[154:157], v[202:205], v[92:95]
	v_mfma_f32_16x16x32_bf16 v[88:91], v[162:165], v[202:205], v[88:91]
	v_mfma_f32_16x16x32_bf16 v[76:79], v[154:157], v[210:213], v[76:79]
	v_mfma_f32_16x16x32_bf16 v[72:75], v[162:165], v[210:213], v[72:75]
	v_mfma_f32_16x16x32_bf16 v[116:119], v[166:169], v[182:185], v[116:119]
	v_mfma_f32_16x16x32_bf16 v[112:115], v[174:177], v[182:185], v[112:115]
	v_mfma_f32_16x16x32_bf16 v[100:103], v[166:169], v[190:193], v[100:103]
	v_mfma_f32_16x16x32_bf16 v[96:99], v[174:177], v[190:193], v[96:99]
	v_mfma_f32_16x16x32_bf16 v[84:87], v[166:169], v[198:201], v[84:87]
	v_mfma_f32_16x16x32_bf16 v[80:83], v[174:177], v[198:201], v[80:83]
	v_mfma_f32_16x16x32_bf16 v[68:71], v[166:169], v[206:209], v[68:71]
	v_mfma_f32_16x16x32_bf16 v[64:67], v[174:177], v[206:209], v[64:67]
	v_mfma_f32_16x16x32_bf16 v[116:119], v[170:173], v[186:189], v[116:119]
	v_mfma_f32_16x16x32_bf16 v[112:115], v[178:181], v[186:189], v[112:115]
	v_mfma_f32_16x16x32_bf16 v[100:103], v[170:173], v[194:197], v[100:103]
	v_mfma_f32_16x16x32_bf16 v[96:99], v[178:181], v[194:197], v[96:99]
	v_mfma_f32_16x16x32_bf16 v[84:87], v[170:173], v[202:205], v[84:87]
	v_mfma_f32_16x16x32_bf16 v[80:83], v[178:181], v[202:205], v[80:83]
	v_mfma_f32_16x16x32_bf16 v[68:71], v[170:173], v[210:213], v[68:71]
	v_mfma_f32_16x16x32_bf16 v[64:67], v[178:181], v[210:213], v[64:67]
	s_setprio 0
	s_barrier
; #define PG8_STAGE(bufoff, gbase, voff) do { _Pragma("unroll") for (int _i = 0; _i < 2; ++_i) \
;         __builtin_amdgcn_global_load_lds((const unsigned*)((const char*)(gbase) + (voff)[_i]), (LAS unsigned*)(lds + (bufoff) + ldsw + _i * 8192), 16, 0, 0); } while (0)
; #define PG8_LDA(dst, b, h) do { _Pragma("unroll") for (int m = 0; m < 4; ++m) _Pragma("unroll") for (int k = 0; k < 2; ++k) dst[m][k] = *(const LAS bf16x8*)(lds + PG8_SA(b, h) + aoff + m * 2048 + k * 1024); } while (0)
; #define PG8_MMA(ai, bj, At, Bt) do { __builtin_amdgcn_s_setprio(1); _Pragma("unroll") for (int m = 0; m < 4; ++m) _Pragma("unroll") for (int n = 0; n < 2; ++n) _Pragma("unroll") for (int k = 0; k < 2; ++k) \
;         acc[ai][bj][m][n] = __builtin_amdgcn_mfma_f32_16x16x32_bf16(Bt[n][k], At[m][k], acc[ai][bj][m][n], 0, 0, 0); __builtin_amdgcn_s_setprio(0); } while (0)
; #define PG8_WAIT_V(n) asm volatile("s_waitcnt vmcnt(" #n ")" ::: "memory")
; #define PG8_WAIT_L(n) asm volatile("s_waitcnt lgkmcnt(" #n ")" ::: "memory")
; #define PG8_BAR __builtin_amdgcn_s_barrier()
; #define PG8_SCHED __builtin_amdgcn_sched_barrier(0)
; template <class Epi, class Sched>
; DI void gemm_phase(LAS unsigned char* lds, const Gemm g, const Sched& S, const Epi& E) {
;     ...
;         for (int t = 0; t < nt; t += 2) {
;             const bool last = (t == nt - 2);
;             const char* a1 = cA + (size_t)(t + 1) * kstep;
;             const char* a2 = last ? nA : cA + (size_t)(t + 2) * kstep; const char* b2 = last ? nB : cB + (size_t)(t + 2) * kstep;
;             const char* a3 = a2 + kstep; const char* b3 = b2 + kstep;
;     ...
;             PG8_LDA(At, 1, 1); PG8_STAGE(PG8_SB(1, 0), b3, voffB); PG8_STAGE(PG8_SB(1, 1), b3 + hstepB, voffB); PG8_STAGE(PG8_SA(1, 0), a3, voffA);
;             PG8_WAIT_V(8); PG8_WAIT_L(0); PG8_BAR; PG8_MMA(1, 0, At, B0); PG8_MMA(1, 1, At, B1); PG8_BAR; PG8_SCHED;
	s_add_i32 s20, s48, s27
	v_lshl_add_u64 v[214:215], v[214:215], 0, s[10:11]
	s_mov_b32 m0, s20
	ds_read_b128 v[182:185], v153 offset:49152
	ds_read_b128 v[186:189], v153 offset:50176
	ds_read_b128 v[190:193], v153 offset:51200
	ds_read_b128 v[194:197], v153 offset:52224
	ds_read_b128 v[198:201], v153 offset:53248
	ds_read_b128 v[202:205], v153 offset:54272
	ds_read_b128 v[206:209], v153 offset:55296
	ds_read_b128 v[210:213], v153 offset:56320
	global_load_lds_dwordx4 v[214:215], off
	s_add_i32 m0, s20, 0x2000
	s_add_u32 s18, s18, 0xb0080
	v_lshl_add_u64 v[214:215], v[216:217], 0, s[10:11]
	s_addc_u32 s19, s19, 0
	s_add_i32 s20, s49, s27
	global_load_lds_dwordx4 v[214:215], off
	v_lshl_add_u64 v[214:215], s[18:19], 0, v[130:131]
	s_mov_b32 m0, s20
	s_nop 0
	global_load_lds_dwordx4 v[214:215], off
	v_lshl_add_u64 v[214:215], s[18:19], 0, v[134:135]
	s_add_i32 m0, s20, 0x2000
	s_nop 0
	global_load_lds_dwordx4 v[214:215], off
	v_lshl_add_u64 v[214:215], v[218:219], 0, s[10:11]
	s_mov_b32 m0, s36
	s_nop 0
	global_load_lds_dwordx4 v[214:215], off
	v_lshl_add_u64 v[214:215], v[220:221], 0, s[10:11]
	s_mov_b32 m0, s37
	s_nop 0
	global_load_lds_dwordx4 v[214:215], off
	s_waitcnt vmcnt(8)
	s_waitcnt lgkmcnt(0)
	s_barrier
	s_setprio 1
	v_mfma_f32_16x16x32_bf16 v[60:63], v[144:147], v[182:185], v[60:63]
	v_mfma_f32_16x16x32_bf16 v[56:59], v[158:161], v[182:185], v[56:59]
	v_mfma_f32_16x16x32_bf16 v[44:47], v[144:147], v[190:193], v[44:47]
	v_mfma_f32_16x16x32_bf16 v[40:43], v[158:161], v[190:193], v[40:43]
	v_mfma_f32_16x16x32_bf16 v[28:31], v[144:147], v[198:201], v[28:31]
	v_mfma_f32_16x16x32_bf16 v[24:27], v[158:161], v[198:201], v[24:27]
	v_mfma_f32_16x16x32_bf16 v[12:15], v[144:147], v[206:209], v[12:15]
	v_mfma_f32_16x16x32_bf16 v[8:11], v[158:161], v[206:209], v[8:11]
	v_mfma_f32_16x16x32_bf16 v[60:63], v[154:157], v[186:189], v[60:63]
	v_mfma_f32_16x16x32_bf16 v[56:59], v[162:165], v[186:189], v[56:59]
	v_mfma_f32_16x16x32_bf16 v[44:47], v[154:157], v[194:197], v[44:47]
	v_mfma_f32_16x16x32_bf16 v[40:43], v[162:165], v[194:197], v[40:43]
	v_mfma_f32_16x16x32_bf16 v[28:31], v[154:157], v[202:205], v[28:31]
	v_mfma_f32_16x16x32_bf16 v[24:27], v[162:165], v[202:205], v[24:27]
	v_mfma_f32_16x16x32_bf16 v[12:15], v[154:157], v[210:213], v[12:15]
	v_mfma_f32_16x16x32_bf16 v[8:11], v[162:165], v[210:213], v[8:11]
	v_mfma_f32_16x16x32_bf16 v[52:55], v[166:169], v[182:185], v[52:55]
	v_mfma_f32_16x16x32_bf16 v[48:51], v[174:177], v[182:185], v[48:51]
	v_mfma_f32_16x16x32_bf16 v[36:39], v[166:169], v[190:193], v[36:39]
	v_mfma_f32_16x16x32_bf16 v[32:35], v[174:177], v[190:193], v[32:35]
	v_mfma_f32_16x16x32_bf16 v[20:23], v[166:169], v[198:201], v[20:23]
	v_mfma_f32_16x16x32_bf16 v[16:19], v[174:177], v[198:201], v[16:19]
	v_mfma_f32_16x16x32_bf16 v[4:7], v[166:169], v[206:209], v[4:7]
	v_mfma_f32_16x16x32_bf16 v[0:3], v[174:177], v[206:209], v[0:3]
	v_mfma_f32_16x16x32_bf16 v[52:55], v[170:173], v[186:189], v[52:55]
	v_mfma_f32_16x16x32_bf16 v[48:51], v[178:181], v[186:189], v[48:51]
	v_mfma_f32_16x16x32_bf16 v[36:39], v[170:173], v[194:197], v[36:39]
	v_mfma_f32_16x16x32_bf16 v[32:35], v[178:181], v[194:197], v[32:35]
	v_mfma_f32_16x16x32_bf16 v[20:23], v[170:173], v[202:205], v[20:23]
	v_mfma_f32_16x16x32_bf16 v[16:19], v[178:181], v[202:205], v[16:19]
	v_mfma_f32_16x16x32_bf16 v[4:7], v[170:173], v[210:213], v[4:7]
	v_mfma_f32_16x16x32_bf16 v[0:3], v[178:181], v[210:213], v[0:3]
	s_setprio 0
	s_barrier
	s_add_i32 s47, s47, 2
	s_add_u32 s16, s16, 0x100
	s_addc_u32 s17, s17, 0
	s_add_u32 s45, s45, 0x100
	s_addc_u32 s46, s46, 0
	s_cmp_gt_u32 s47, 41
	.p2alignl 6, 3212836864
